# hand-written 256x128 k-loops: priority 1 while the wave issues its fragment reads and the next slice's LDS-DMA, priority 0 for the rest (the seed's memory-issue window restored)
# speedup vs baseline: 1.0125x; 1.0062x over previous
; template <int MI, int NI>
; DI void gemm256(f32x4 (&acc)[MI][NI], const u16* __restrict__ A, int lda, const u16* __restrict__ Bt, int ldb, int K, int m0, int n0, char* smem) {
;     ...
;   for (int kt = 0; kt < nk; ++kt) {
;     if (kt + 1 < nk) asm volatile("s_waitcnt vmcnt(%0) lgkmcnt(0)" :: "n"(LPS) : "memory");
;     else asm volatile("s_waitcnt vmcnt(0) lgkmcnt(0)" ::: "memory");
;     __builtin_amdgcn_s_barrier();
;     __builtin_amdgcn_s_setprio(1);
;     const char* sb = smem + st * STAGE + foff;
;     bf16x8 af[MI], bfr[NI];
; #pragma unroll
;     for (int mi = 0; mi < MI; ++mi) af[mi] = *(const bf16x8*)(sb + (wr * MI + mi) * 1024);
; #pragma unroll
;     for (int ni = 0; ni < NI; ++ni) bfr[ni] = *(const bf16x8*)(sb + ABYTES + (wc * NI + ni) * 1024);
;     __builtin_amdgcn_sched_barrier(0x0);
;     if (kt + 2 < nk) { const int s2 = st >= 1 ? st - 1 : 2; G256_ISSUE(s2, (kt + 2) * 32); }
;     __builtin_amdgcn_s_setprio(0);
; #pragma unroll
;     for (int mi = 0; mi < MI; ++mi)
; #pragma unroll
;       for (int ni = 0; ni < NI; ++ni)
;         acc[mi][ni] = __builtin_amdgcn_mfma_f32_16x16x32_bf16(bfr[ni], af[mi], acc[mi][ni], 0, 0, 0);
;     st = st == 2 ? 0 : st + 1;
;   }
.Lpipe_mlp1:
	s_setprio 1
	v_add_u32_e32 v160, s11, v143
	ds_read_b128 v[164:167], v160 offset:4096
	ds_read_b128 v[168:171], v160 offset:5120
	ds_read_b128 v[172:175], v160 offset:6144
	ds_read_b128 v[176:179], v160 offset:7168
	s_add_i32 s12, s11, 0xffffa000
	s_cmp_eq_u32 s11, 0
	s_cselect_b32 s12, 0xc000, s12
	s_add_i32 s13, s12, s14
	s_add_i32 s12, s12, s4
	s_mov_b32 m0, s13
	s_waitcnt lgkmcnt(7)
	v_mfma_f32_16x16x32_bf16 v[126:129], v[180:183], v[144:147], v[126:129]
	global_load_lds_dwordx4 v[198:199], off
	v_mfma_f32_16x16x32_bf16 v[110:113], v[180:183], v[148:151], v[110:113]
	v_lshl_add_u64 v[198:199], v[198:199], 0, s[98:99]
	s_add_i32 m0, s13, 0x400
	v_mfma_f32_16x16x32_bf16 v[94:97], v[180:183], v[152:155], v[94:97]
	global_load_lds_dwordx4 v[200:201], off
	v_mfma_f32_16x16x32_bf16 v[78:81], v[180:183], v[156:159], v[78:81]
	v_lshl_add_u64 v[200:201], v[200:201], 0, s[98:99]
	s_add_i32 m0, s13, 0x800
	s_waitcnt lgkmcnt(6)
	v_mfma_f32_16x16x32_bf16 v[122:125], v[184:187], v[144:147], v[122:125]
	global_load_lds_dwordx4 v[202:203], off
	v_mfma_f32_16x16x32_bf16 v[106:109], v[184:187], v[148:151], v[106:109]
	v_lshl_add_u64 v[202:203], v[202:203], 0, s[98:99]
	s_add_i32 m0, s13, 0xc00
	v_mfma_f32_16x16x32_bf16 v[90:93], v[184:187], v[152:155], v[90:93]
	global_load_lds_dwordx4 v[204:205], off
	v_mfma_f32_16x16x32_bf16 v[74:77], v[184:187], v[156:159], v[74:77]
	v_lshl_add_u64 v[204:205], v[204:205], 0, s[98:99]
	s_mov_b32 m0, s12
	s_waitcnt lgkmcnt(5)
	v_mfma_f32_16x16x32_bf16 v[118:121], v[188:191], v[144:147], v[118:121]
	global_load_lds_dwordx4 v[206:207], off
	v_mfma_f32_16x16x32_bf16 v[102:105], v[188:191], v[148:151], v[102:105]
	v_lshl_add_u64 v[206:207], v[206:207], 0, s[98:99]
	s_add_i32 m0, s12, 0x400
	v_mfma_f32_16x16x32_bf16 v[86:89], v[188:191], v[152:155], v[86:89]
	global_load_lds_dwordx4 v[208:209], off
	v_mfma_f32_16x16x32_bf16 v[70:73], v[188:191], v[156:159], v[70:73]
	v_lshl_add_u64 v[208:209], v[208:209], 0, s[98:99]
	s_setprio 0
	s_waitcnt lgkmcnt(4)
	v_mfma_f32_16x16x32_bf16 v[114:117], v[192:195], v[144:147], v[114:117]
	v_mfma_f32_16x16x32_bf16 v[98:101], v[192:195], v[148:151], v[98:101]
	v_mfma_f32_16x16x32_bf16 v[82:85], v[192:195], v[152:155], v[82:85]
	v_mfma_f32_16x16x32_bf16 v[66:69], v[192:195], v[156:159], v[66:69]
	s_waitcnt vmcnt(6) lgkmcnt(0)
	s_barrier
	s_add_i32 s13, s11, 0x6000
	s_cmp_eq_u32 s11, 0xc000
	s_cselect_b32 s11, 0, s13
	v_add_u32_e32 v196, s11, v143
	v_add_u32_e32 v197, s11, v0
	v_mfma_f32_16x16x32_bf16 v[62:65], v[180:183], v[164:167], v[62:65]
	ds_read_b128 v[144:147], v196
	v_mfma_f32_16x16x32_bf16 v[46:49], v[180:183], v[168:171], v[46:49]
	ds_read_b128 v[148:151], v196 offset:1024
	v_mfma_f32_16x16x32_bf16 v[30:33], v[180:183], v[172:175], v[30:33]
	ds_read_b128 v[152:155], v196 offset:2048
	v_mfma_f32_16x16x32_bf16 v[14:17], v[180:183], v[176:179], v[14:17]
	ds_read_b128 v[156:159], v196 offset:3072
	ds_read_b128 v[180:183], v197 offset:16384
	v_mfma_f32_16x16x32_bf16 v[58:61], v[184:187], v[164:167], v[58:61]
	v_mfma_f32_16x16x32_bf16 v[42:45], v[184:187], v[168:171], v[42:45]
	v_mfma_f32_16x16x32_bf16 v[26:29], v[184:187], v[172:175], v[26:29]
	v_mfma_f32_16x16x32_bf16 v[10:13], v[184:187], v[176:179], v[10:13]
	ds_read_b128 v[184:187], v197 offset:17408
	v_mfma_f32_16x16x32_bf16 v[54:57], v[188:191], v[164:167], v[54:57]
	v_mfma_f32_16x16x32_bf16 v[38:41], v[188:191], v[168:171], v[38:41]
	v_mfma_f32_16x16x32_bf16 v[22:25], v[188:191], v[172:175], v[22:25]
	v_mfma_f32_16x16x32_bf16 v[6:9], v[188:191], v[176:179], v[6:9]
	ds_read_b128 v[188:191], v197 offset:18432
	v_mfma_f32_16x16x32_bf16 v[50:53], v[192:195], v[164:167], v[50:53]
	v_mfma_f32_16x16x32_bf16 v[34:37], v[192:195], v[168:171], v[34:37]
	v_mfma_f32_16x16x32_bf16 v[18:21], v[192:195], v[172:175], v[18:21]
	v_mfma_f32_16x16x32_bf16 v[2:5], v[192:195], v[176:179], v[2:5]
	ds_read_b128 v[192:195], v197 offset:19456
	s_sub_i32 s5, s5, 1
	s_cmp_lg_u32 s5, 0
	s_cbranch_scc1 .Lpipe_mlp1
	v_add_u32_e32 v160, s11, v143
	ds_read_b128 v[164:167], v160 offset:4096
	ds_read_b128 v[168:171], v160 offset:5120
	ds_read_b128 v[172:175], v160 offset:6144
	ds_read_b128 v[176:179], v160 offset:7168
	s_add_i32 s12, s11, 0xffffa000
	s_cmp_eq_u32 s11, 0
	s_cselect_b32 s12, 0xc000, s12
	s_add_i32 s13, s12, s14
	s_add_i32 s12, s12, s4
	s_mov_b32 m0, s13
	s_waitcnt lgkmcnt(7)
	v_mfma_f32_16x16x32_bf16 v[126:129], v[180:183], v[144:147], v[126:129]
	global_load_lds_dwordx4 v[198:199], off
	v_mfma_f32_16x16x32_bf16 v[110:113], v[180:183], v[148:151], v[110:113]
	v_lshl_add_u64 v[198:199], v[198:199], 0, s[98:99]
	s_add_i32 m0, s13, 0x400
	v_mfma_f32_16x16x32_bf16 v[94:97], v[180:183], v[152:155], v[94:97]
	global_load_lds_dwordx4 v[200:201], off
	v_mfma_f32_16x16x32_bf16 v[78:81], v[180:183], v[156:159], v[78:81]
	v_lshl_add_u64 v[200:201], v[200:201], 0, s[98:99]
	s_add_i32 m0, s13, 0x800
	s_waitcnt lgkmcnt(6)
	v_mfma_f32_16x16x32_bf16 v[122:125], v[184:187], v[144:147], v[122:125]
	global_load_lds_dwordx4 v[202:203], off
	v_mfma_f32_16x16x32_bf16 v[106:109], v[184:187], v[148:151], v[106:109]
	v_lshl_add_u64 v[202:203], v[202:203], 0, s[98:99]
	s_add_i32 m0, s13, 0xc00
	v_mfma_f32_16x16x32_bf16 v[90:93], v[184:187], v[152:155], v[90:93]
	global_load_lds_dwordx4 v[204:205], off
	v_mfma_f32_16x16x32_bf16 v[74:77], v[184:187], v[156:159], v[74:77]
	v_lshl_add_u64 v[204:205], v[204:205], 0, s[98:99]
	s_mov_b32 m0, s12
	s_waitcnt lgkmcnt(5)
; template <int MI, int NI>
; DI void gemm256(f32x4 (&acc)[MI][NI], const u16* __restrict__ A, int lda, const u16* __restrict__ Bt, int ldb, int K, int m0, int n0, char* smem) {
;     ...
;   for (int kt = 0; kt < nk; ++kt) {
;     if (kt + 1 < nk) asm volatile("s_waitcnt vmcnt(%0) lgkmcnt(0)" :: "n"(LPS) : "memory");
;     else asm volatile("s_waitcnt vmcnt(0) lgkmcnt(0)" ::: "memory");
;     __builtin_amdgcn_s_barrier();
;     __builtin_amdgcn_s_setprio(1);
;     const char* sb = smem + st * STAGE + foff;
;     bf16x8 af[MI], bfr[NI];
; #pragma unroll
;     for (int mi = 0; mi < MI; ++mi) af[mi] = *(const bf16x8*)(sb + (wr * MI + mi) * 1024);
; #pragma unroll
;     for (int ni = 0; ni < NI; ++ni) bfr[ni] = *(const bf16x8*)(sb + ABYTES + (wc * NI + ni) * 1024);
;     __builtin_amdgcn_sched_barrier(0x0);
;     if (kt + 2 < nk) { const int s2 = st >= 1 ? st - 1 : 2; G256_ISSUE(s2, (kt + 2) * 32); }
;     __builtin_amdgcn_s_setprio(0);
; #pragma unroll
;     for (int mi = 0; mi < MI; ++mi)
; #pragma unroll
;       for (int ni = 0; ni < NI; ++ni)
;         acc[mi][ni] = __builtin_amdgcn_mfma_f32_16x16x32_bf16(bfr[ni], af[mi], acc[mi][ni], 0, 0, 0);
;     st = st == 2 ? 0 : st + 1;
;   }
;   asm volatile("s_waitcnt lgkmcnt(0)" ::: "memory");
;   __builtin_amdgcn_s_barrier();
	v_mfma_f32_16x16x32_bf16 v[118:121], v[188:191], v[144:147], v[118:121]
	global_load_lds_dwordx4 v[206:207], off
	v_mfma_f32_16x16x32_bf16 v[102:105], v[188:191], v[148:151], v[102:105]
	v_lshl_add_u64 v[206:207], v[206:207], 0, s[98:99]
	s_add_i32 m0, s12, 0x400
	v_mfma_f32_16x16x32_bf16 v[86:89], v[188:191], v[152:155], v[86:89]
	global_load_lds_dwordx4 v[208:209], off
	v_mfma_f32_16x16x32_bf16 v[70:73], v[188:191], v[156:159], v[70:73]
	v_lshl_add_u64 v[208:209], v[208:209], 0, s[98:99]
	s_waitcnt lgkmcnt(4)
	v_mfma_f32_16x16x32_bf16 v[114:117], v[192:195], v[144:147], v[114:117]
	v_mfma_f32_16x16x32_bf16 v[98:101], v[192:195], v[148:151], v[98:101]
	v_mfma_f32_16x16x32_bf16 v[82:85], v[192:195], v[152:155], v[82:85]
	v_mfma_f32_16x16x32_bf16 v[66:69], v[192:195], v[156:159], v[66:69]
	s_waitcnt lgkmcnt(0)
	v_mfma_f32_16x16x32_bf16 v[62:65], v[180:183], v[164:167], v[62:65]
	v_mfma_f32_16x16x32_bf16 v[46:49], v[180:183], v[168:171], v[46:49]
	v_mfma_f32_16x16x32_bf16 v[30:33], v[180:183], v[172:175], v[30:33]
	v_mfma_f32_16x16x32_bf16 v[14:17], v[180:183], v[176:179], v[14:17]
	v_mfma_f32_16x16x32_bf16 v[58:61], v[184:187], v[164:167], v[58:61]
	v_mfma_f32_16x16x32_bf16 v[42:45], v[184:187], v[168:171], v[42:45]
	v_mfma_f32_16x16x32_bf16 v[26:29], v[184:187], v[172:175], v[26:29]
	v_mfma_f32_16x16x32_bf16 v[10:13], v[184:187], v[176:179], v[10:13]
	v_mfma_f32_16x16x32_bf16 v[54:57], v[188:191], v[164:167], v[54:57]
	v_mfma_f32_16x16x32_bf16 v[38:41], v[188:191], v[168:171], v[38:41]
	v_mfma_f32_16x16x32_bf16 v[22:25], v[188:191], v[172:175], v[22:25]
	v_mfma_f32_16x16x32_bf16 v[6:9], v[188:191], v[176:179], v[6:9]
	v_mfma_f32_16x16x32_bf16 v[50:53], v[192:195], v[164:167], v[50:53]
	v_mfma_f32_16x16x32_bf16 v[34:37], v[192:195], v[168:171], v[34:37]
	v_mfma_f32_16x16x32_bf16 v[18:21], v[192:195], v[172:175], v[18:21]
	v_mfma_f32_16x16x32_bf16 v[2:5], v[192:195], v[176:179], v[2:5]
	s_waitcnt vmcnt(6) lgkmcnt(0)
	s_barrier
	s_setprio 1
	v_add_u32_e32 v0, v140, v142
	ds_read_b128 v[130:133], v0
	ds_read_b128 v[142:145], v0 offset:1024
	ds_read_b128 v[146:149], v0 offset:2048
	ds_read_b128 v[150:153], v0 offset:3072
	ds_read_b128 v[154:157], v0 offset:4096
	ds_read_b128 v[158:161], v0 offset:5120
	ds_read_b128 v[164:167], v0 offset:6144
	ds_read_b128 v[168:171], v0 offset:7168
	v_add_u32_e32 v212, v140, v141
	ds_read_b128 v[138:141], v212 offset:16384
	ds_read_b128 v[172:175], v212 offset:17408
	ds_read_b128 v[176:179], v212 offset:18432
	ds_read_b128 v[180:183], v212 offset:19456
	s_setprio 0
	s_waitcnt vmcnt(0) lgkmcnt(0)
	s_waitcnt lgkmcnt(3)
	v_mfma_f32_16x16x32_bf16 v[126:129], v[138:141], v[130:133], v[126:129]
	s_barrier
	s_waitcnt lgkmcnt(2)
	v_mfma_f32_16x16x32_bf16 v[122:125], v[172:175], v[130:133], v[122:125]
	s_waitcnt lgkmcnt(1)
	v_mfma_f32_16x16x32_bf16 v[184:187], v[176:179], v[130:133], v[118:121]
	s_waitcnt lgkmcnt(0)
	v_mfma_f32_16x16x32_bf16 v[114:117], v[180:183], v[130:133], v[114:117]
	v_mfma_f32_16x16x32_bf16 v[130:133], v[138:141], v[142:145], v[110:113]
	v_mfma_f32_16x16x32_bf16 v[106:109], v[172:175], v[142:145], v[106:109]
	v_mfma_f32_16x16x32_bf16 v[188:191], v[176:179], v[142:145], v[102:105]
	v_mfma_f32_16x16x32_bf16 v[98:101], v[180:183], v[142:145], v[98:101]
	v_mfma_f32_16x16x32_bf16 v[94:97], v[138:141], v[146:149], v[94:97]
	v_mfma_f32_16x16x32_bf16 v[90:93], v[172:175], v[146:149], v[90:93]
	v_mfma_f32_16x16x32_bf16 v[142:145], v[176:179], v[146:149], v[86:89]
	v_mfma_f32_16x16x32_bf16 v[82:85], v[180:183], v[146:149], v[82:85]
	v_mfma_f32_16x16x32_bf16 v[146:149], v[138:141], v[150:153], v[78:81]
	v_mfma_f32_16x16x32_bf16 v[74:77], v[172:175], v[150:153], v[74:77]
	v_mfma_f32_16x16x32_bf16 v[192:195], v[176:179], v[150:153], v[70:73]
	v_mfma_f32_16x16x32_bf16 v[66:69], v[180:183], v[150:153], v[66:69]
	v_mfma_f32_16x16x32_bf16 v[62:65], v[138:141], v[154:157], v[62:65]
	v_mfma_f32_16x16x32_bf16 v[58:61], v[172:175], v[154:157], v[58:61]
	v_mfma_f32_16x16x32_bf16 v[150:153], v[176:179], v[154:157], v[54:57]
	v_mfma_f32_16x16x32_bf16 v[50:53], v[180:183], v[154:157], v[50:53]
	v_mfma_f32_16x16x32_bf16 v[154:157], v[138:141], v[158:161], v[46:49]
	v_mfma_f32_16x16x32_bf16 v[42:45], v[172:175], v[158:161], v[42:45]
	v_mfma_f32_16x16x32_bf16 v[196:199], v[176:179], v[158:161], v[38:41]
	v_mfma_f32_16x16x32_bf16 v[34:37], v[180:183], v[158:161], v[34:37]
	v_mfma_f32_16x16x32_bf16 v[30:33], v[138:141], v[164:167], v[30:33]
	v_mfma_f32_16x16x32_bf16 v[26:29], v[172:175], v[164:167], v[26:29]
	v_mfma_f32_16x16x32_bf16 v[158:161], v[176:179], v[164:167], v[22:25]
	v_mfma_f32_16x16x32_bf16 v[18:21], v[180:183], v[164:167], v[18:21]
	v_mfma_f32_16x16x32_bf16 v[138:141], v[138:141], v[168:171], v[14:17]
	v_mfma_f32_16x16x32_bf16 v[10:13], v[172:175], v[168:171], v[10:13]
	v_mfma_f32_16x16x32_bf16 v[164:167], v[176:179], v[168:171], v[6:9]
	v_mfma_f32_16x16x32_bf16 v[2:5], v[180:183], v[168:171], v[2:5]
	s_setprio 1
	s_nop 0
	ds_read_b128 v[6:9], v0 offset:24576
	ds_read_b128 v[14:17], v0 offset:25600
	ds_read_b128 v[22:25], v0 offset:26624
	ds_read_b128 v[38:41], v0 offset:27648
	ds_read_b128 v[168:171], v0 offset:28672
	ds_read_b128 v[172:175], v0 offset:29696
	ds_read_b128 v[176:179], v0 offset:30720
	ds_read_b128 v[180:183], v0 offset:31744
	ds_read_b128 v[200:203], v212 offset:40960
	ds_read_b128 v[204:207], v212 offset:41984
	ds_read_b128 v[208:211], v212 offset:43008
	ds_read_b128 v[212:215], v212 offset:44032
	s_setprio 0
	s_waitcnt lgkmcnt(3)
	v_mfma_f32_16x16x32_bf16 v[216:219], v[200:203], v[6:9], v[126:129]
	v_mov_b32_e32 v0, v136
	s_waitcnt lgkmcnt(0)
	s_barrier
; DI unsigned pack2(float a, float b) { float2_t v = {a, b}; bf16x2_t r = __builtin_convertvector(v, bf16x2_t); return __builtin_bit_cast(unsigned, r); }
; template <int MI, int NI>
; DI void gemm256(f32x4 (&acc)[MI][NI], const u16* __restrict__ A, int lda, const u16* __restrict__ Bt, int ldb, int K, int m0, int n0, char* smem) {
;     ...
; #pragma unroll
;     for (int mi = 0; mi < MI; ++mi)
; #pragma unroll
;       for (int ni = 0; ni < NI; ++ni)
;         acc[mi][ni] = __builtin_amdgcn_mfma_f32_16x16x32_bf16(bfr[ni], af[mi], acc[mi][ni], 0, 0, 0);
; DI void phase_mlp1(const Params& p, int l, int Mout, char* smem) {
;     ...
; #pragma unroll
;     for (int mi = 0; mi < 8; mi += 2) {
;       const int m = m0 + wr * 128 + (mi + (lq & 1)) * 16 + lr;
; #pragma unroll
;       for (int ni = 0; ni < 4; ++ni) {
;         const int n = n0 + wc * 64 + ni * 16 + (lq >> 1) * 8;
;         float va[4], vb[4];
; #pragma unroll
;         for (int j = 0; j < 4; ++j) { const float a = fmaxf(acc[mi][ni][j], 0.f); va[j] = a * a; const float b = fmaxf(acc[mi + 1][ni][j], 0.f); vb[j] = b * b; }
;         *(uint4*)(U + (size_t)m * DFF + n) = widen16(make_uint2(pack2(va[0], va[1]), pack2(va[2], va[3])), make_uint2(pack2(vb[0], vb[1]), pack2(vb[2], vb[3])));
;       }
;       __builtin_amdgcn_sched_barrier(0);
;     }
	s_waitcnt lgkmcnt(2)
	v_mfma_f32_16x16x32_bf16 v[118:121], v[204:207], v[6:9], v[122:125]
	v_mov_b32_e32 v126, v137
	v_mov_b32_e32 v127, v134
	v_lshlrev_b32_e32 v129, 2, v126
	v_lshlrev_b32_e32 v126, 4, v126
	v_mfma_f32_16x16x32_bf16 v[122:125], v[200:203], v[14:17], v[130:133]
	v_mov_b32_e32 v128, v135
	v_lshlrev_b32_e32 v127, 7, v127
	v_add_u32_e32 v0, s10, v0
	v_and_b32_e32 v126, 16, v126
	v_add3_u32 v126, v0, v127, v126
	v_lshlrev_b32_e32 v128, 6, v128
	v_and_b32_e32 v129, -8, v129
	v_ashrrev_i32_e32 v127, 31, v126
	v_add3_u32 v132, v129, s9, v128
	v_and_b32_e32 v220, 1, v126
	v_lshrrev_b32_e32 v128, 1, v126
	v_mov_b32_e32 v129, 0
	v_lshlrev_b64 v[128:129], 14, v[128:129]
	v_lshl_or_b32 v128, v220, 6, v128
	v_max_f32_e32 v0, v216, v216
	v_mfma_f32_16x16x32_bf16 v[94:97], v[200:203], v[22:25], v[94:97]
	v_ashrrev_i32_e32 v133, 31, v132
	v_mfma_f32_16x16x32_bf16 v[86:89], v[204:207], v[22:25], v[90:93]
	s_waitcnt lgkmcnt(1)
	v_mfma_f32_16x16x32_bf16 v[78:81], v[208:211], v[22:25], v[142:145]
	s_waitcnt lgkmcnt(0)
	v_mfma_f32_16x16x32_bf16 v[70:73], v[212:215], v[22:25], v[82:85]
	v_mfma_f32_16x16x32_bf16 v[22:25], v[204:207], v[176:179], v[26:29]
	v_mfma_f32_16x16x32_bf16 v[26:29], v[200:203], v[180:183], v[138:141]
	s_nop 2
	v_lshl_add_u64 v[138:139], s[60:61], 0, v[128:129]
	v_max_f32_e32 v128, 0, v0
	v_max_f32_e32 v0, v122, v122
	v_max_f32_e32 v122, 0, v0
	v_max_f32_e32 v0, v217, v217
	v_max_f32_e32 v129, 0, v0
	v_max_f32_e32 v0, v123, v123
	v_max_f32_e32 v123, 0, v0
	v_max_f32_e32 v0, v218, v218
	v_mfma_f32_16x16x32_bf16 v[102:105], v[212:215], v[6:9], v[114:117]
	v_max_f32_e32 v130, 0, v0
	v_max_f32_e32 v0, v124, v124
	v_max_f32_e32 v124, 0, v0
	v_mfma_f32_16x16x32_bf16 v[114:117], v[204:207], v[14:17], v[106:109]
	v_max_f32_e32 v0, v219, v219
	v_max_f32_e32 v131, 0, v0
	v_max_f32_e32 v0, v125, v125
	v_max_f32_e32 v125, 0, v0
	v_max_f32_e32 v0, v118, v118
	v_max_f32_e32 v118, 0, v0
	s_nop 1
	v_max_f32_e32 v0, v114, v114
	v_pk_mul_f32 v[128:129], v[128:129], v[128:129]
	v_pk_mul_f32 v[122:123], v[122:123], v[122:123]
	v_pk_mul_f32 v[130:131], v[130:131], v[130:131]
	v_pk_mul_f32 v[124:125], v[124:125], v[124:125]
	v_max_f32_e32 v114, 0, v0
	v_max_f32_e32 v0, v119, v119
	v_cvt_pk_bf16_f32 v128, v128, v129
	v_cvt_pk_bf16_f32 v129, v130, v131
	v_cvt_pk_bf16_f32 v130, v122, v123
	v_cvt_pk_bf16_f32 v131, v124, v125
	v_and_b32_e32 v220, 31, v132
	v_lshrrev_b32_e32 v122, 5, v132
	v_lshlrev_b32_e32 v122, 7, v122
	v_lshl_or_b32 v122, v220, 1, v122
	v_mov_b32_e32 v123, 0
	v_max_f32_e32 v119, 0, v0
	v_max_f32_e32 v0, v115, v115
	v_mfma_f32_16x16x32_bf16 v[110:113], v[208:211], v[6:9], v[184:187]
	v_permlane16_swap_b32_e32 v128, v130
	v_permlane16_swap_b32_e32 v129, v131
	v_lshl_add_u64 v[124:125], v[138:139], 0, v[122:123]
	v_max_f32_e32 v115, 0, v0
	v_max_f32_e32 v0, v120, v120
	v_mfma_f32_16x16x32_bf16 v[106:109], v[208:211], v[14:17], v[188:191]
	flat_store_dwordx4 v[124:125], v[128:131]
	v_pk_mul_f32 v[118:119], v[118:119], v[118:119]
	s_nop 0
	v_pk_mul_f32 v[128:129], v[114:115], v[114:115]
	v_max_f32_e32 v114, 0, v0
	v_max_f32_e32 v0, v116, v116
	v_max_f32_e32 v116, 0, v0
	v_max_f32_e32 v0, v121, v121
	v_max_f32_e32 v115, 0, v0
	v_max_f32_e32 v0, v117, v117
	v_max_f32_e32 v117, 0, v0
	v_max_f32_e32 v0, v110, v110
	v_max_f32_e32 v110, 0, v0
	v_max_f32_e32 v0, v106, v106
	v_pk_mul_f32 v[120:121], v[114:115], v[114:115]
	v_pk_mul_f32 v[130:131], v[116:117], v[116:117]
	v_max_f32_e32 v106, 0, v0
	v_max_f32_e32 v0, v111, v111
	v_cvt_pk_bf16_f32 v114, v118, v119
	v_cvt_pk_bf16_f32 v115, v120, v121
	v_cvt_pk_bf16_f32 v116, v128, v129
	v_cvt_pk_bf16_f32 v117, v130, v131
	v_max_f32_e32 v111, 0, v0
	v_max_f32_e32 v0, v107, v107
	v_permlane16_swap_b32_e32 v114, v116
	v_permlane16_swap_b32_e32 v115, v117
	v_max_f32_e32 v107, 0, v0
	v_max_f32_e32 v0, v112, v112
	v_mfma_f32_16x16x32_bf16 v[98:101], v[212:215], v[14:17], v[98:101]
	flat_store_dwordx4 v[124:125], v[114:117] offset:32
	v_pk_mul_f32 v[110:111], v[110:111], v[110:111]
	s_nop 0
	v_pk_mul_f32 v[114:115], v[106:107], v[106:107]
	v_max_f32_e32 v106, 0, v0
	v_max_f32_e32 v0, v108, v108
	v_max_f32_e32 v108, 0, v0
	v_max_f32_e32 v0, v113, v113
	v_max_f32_e32 v107, 0, v0
	v_max_f32_e32 v0, v109, v109
	v_max_f32_e32 v109, 0, v0
	v_max_f32_e32 v0, v102, v102
	v_max_f32_e32 v102, 0, v0
	v_max_f32_e32 v0, v98, v98
	v_pk_mul_f32 v[112:113], v[106:107], v[106:107]
	v_pk_mul_f32 v[116:117], v[108:109], v[108:109]
	v_max_f32_e32 v98, 0, v0
	v_max_f32_e32 v0, v103, v103
	v_cvt_pk_bf16_f32 v106, v110, v111
	v_cvt_pk_bf16_f32 v107, v112, v113
	v_cvt_pk_bf16_f32 v108, v114, v115
	v_cvt_pk_bf16_f32 v109, v116, v117
	v_max_f32_e32 v103, 0, v0
	v_max_f32_e32 v0, v99, v99
	v_permlane16_swap_b32_e32 v106, v108
	v_permlane16_swap_b32_e32 v107, v109
	v_max_f32_e32 v99, 0, v0
	v_max_f32_e32 v0, v104, v104
	flat_store_dwordx4 v[124:125], v[106:109] offset:128
	v_pk_mul_f32 v[102:103], v[102:103], v[102:103]
	v_mfma_f32_16x16x32_bf16 v[90:93], v[200:203], v[38:41], v[146:149]
	v_mul_f32_e64 v106, v98, v98
	v_mul_f32_e64 v107, v99, v99
	v_max_f32_e32 v98, 0, v0
	v_max_f32_e32 v0, v100, v100
	v_max_f32_e32 v100, 0, v0
	v_max_f32_e32 v0, v105, v105
	v_max_f32_e32 v99, 0, v0
	v_max_f32_e32 v0, v101, v101
	v_max_f32_e32 v101, 0, v0
	v_pk_mul_f32 v[104:105], v[98:99], v[98:99]
	v_pk_mul_f32 v[108:109], v[100:101], v[100:101]
	v_cvt_pk_bf16_f32 v98, v102, v103
	v_cvt_pk_bf16_f32 v99, v104, v105
	v_cvt_pk_bf16_f32 v100, v106, v107
	v_cvt_pk_bf16_f32 v101, v108, v109
	s_nop 0
	v_permlane16_swap_b32_e32 v98, v100
	v_permlane16_swap_b32_e32 v99, v101
	v_mfma_f32_16x16x32_bf16 v[82:85], v[204:207], v[38:41], v[74:77]
; DI unsigned pack2(float a, float b) { float2_t v = {a, b}; bf16x2_t r = __builtin_convertvector(v, bf16x2_t); return __builtin_bit_cast(unsigned, r); }
; DI void phase_mlp1(const Params& p, int l, int Mout, char* smem) {
;     ...
; #pragma unroll
;     for (int mi = 0; mi < 8; mi += 2) {
;       const int m = m0 + wr * 128 + (mi + (lq & 1)) * 16 + lr;
; #pragma unroll
;       for (int ni = 0; ni < 4; ++ni) {
;         const int n = n0 + wc * 64 + ni * 16 + (lq >> 1) * 8;
;         float va[4], vb[4];
; #pragma unroll
;         for (int j = 0; j < 4; ++j) { const float a = fmaxf(acc[mi][ni][j], 0.f); va[j] = a * a; const float b = fmaxf(acc[mi + 1][ni][j], 0.f); vb[j] = b * b; }
;         *(uint4*)(U + (size_t)m * DFF + n) = widen16(make_uint2(pack2(va[0], va[1]), pack2(va[2], va[3])), make_uint2(pack2(vb[0], vb[1]), pack2(vb[2], vb[3])));
;       }
;       __builtin_amdgcn_sched_barrier(0);
;     }
	flat_store_dwordx4 v[124:125], v[98:101] offset:160
	v_mfma_f32_16x16x32_bf16 v[74:77], v[208:211], v[38:41], v[192:195]
	v_mfma_f32_16x16x32_bf16 v[66:69], v[212:215], v[38:41], v[66:69]
	v_mfma_f32_16x16x32_bf16 v[62:65], v[200:203], v[168:171], v[62:65]
	v_mfma_f32_16x16x32_bf16 v[54:57], v[204:207], v[168:171], v[58:61]
	v_mfma_f32_16x16x32_bf16 v[46:49], v[208:211], v[168:171], v[150:153]
	v_mfma_f32_16x16x32_bf16 v[38:41], v[212:215], v[168:171], v[50:53]
	v_mfma_f32_16x16x32_bf16 v[58:61], v[200:203], v[172:175], v[154:157]
	v_mfma_f32_16x16x32_bf16 v[50:53], v[204:207], v[172:175], v[42:45]
	v_mfma_f32_16x16x32_bf16 v[42:45], v[208:211], v[172:175], v[196:199]
	v_mfma_f32_16x16x32_bf16 v[34:37], v[212:215], v[172:175], v[34:37]
	v_mfma_f32_16x16x32_bf16 v[30:33], v[200:203], v[176:179], v[30:33]
	v_mfma_f32_16x16x32_bf16 v[14:17], v[208:211], v[176:179], v[158:161]
	v_mfma_f32_16x16x32_bf16 v[6:9], v[212:215], v[176:179], v[18:21]
	v_mfma_f32_16x16x32_bf16 v[18:21], v[204:207], v[180:183], v[10:13]
	v_mfma_f32_16x16x32_bf16 v[10:13], v[208:211], v[180:183], v[164:167]
	v_mfma_f32_16x16x32_bf16 v[2:5], v[212:215], v[180:183], v[2:5]
	v_max_f32_e32 v0, v94, v94
	v_max_f32_e32 v94, 0, v0
	v_max_f32_e32 v0, v90, v90
	v_max_f32_e32 v90, 0, v0
	v_max_f32_e32 v0, v95, v95
	v_max_f32_e32 v95, 0, v0
	v_max_f32_e32 v0, v91, v91
	v_max_f32_e32 v91, 0, v0
	v_max_f32_e32 v0, v96, v96
	v_pk_mul_f32 v[100:101], v[90:91], v[90:91]
	v_max_f32_e32 v90, 0, v0
	v_max_f32_e32 v0, v92, v92
	v_max_f32_e32 v92, 0, v0
	v_max_f32_e32 v0, v97, v97
	v_max_f32_e32 v91, 0, v0
	v_max_f32_e32 v0, v93, v93
	v_add_u32_e32 v98, 32, v126
	v_max_f32_e32 v93, 0, v0
	v_max_f32_e32 v0, v86, v86
	v_ashrrev_i32_e32 v99, 31, v98
	v_max_f32_e32 v86, 0, v0
	v_max_f32_e32 v0, v82, v82
	v_and_b32_e32 v220, 1, v98
	v_lshrrev_b32_e32 v98, 1, v98
	v_mov_b32_e32 v99, 0
	v_lshlrev_b64 v[98:99], 14, v[98:99]
	v_lshl_or_b32 v98, v220, 6, v98
	v_pk_mul_f32 v[94:95], v[94:95], v[94:95]
	v_pk_mul_f32 v[96:97], v[90:91], v[90:91]
	v_pk_mul_f32 v[102:103], v[92:93], v[92:93]
	v_max_f32_e32 v82, 0, v0
	v_max_f32_e32 v0, v87, v87
	v_lshl_add_u64 v[98:99], s[60:61], 0, v[98:99]
	v_cvt_pk_bf16_f32 v90, v94, v95
	v_cvt_pk_bf16_f32 v91, v96, v97
	v_cvt_pk_bf16_f32 v92, v100, v101
	v_cvt_pk_bf16_f32 v93, v102, v103
	v_max_f32_e32 v87, 0, v0
	v_max_f32_e32 v0, v83, v83
	v_permlane16_swap_b32_e32 v90, v92
	v_permlane16_swap_b32_e32 v91, v93
	v_lshl_add_u64 v[94:95], v[98:99], 0, v[122:123]
	v_max_f32_e32 v83, 0, v0
	v_max_f32_e32 v0, v88, v88
	flat_store_dwordx4 v[94:95], v[90:93]
	v_pk_mul_f32 v[86:87], v[86:87], v[86:87]
	s_nop 0
	v_pk_mul_f32 v[90:91], v[82:83], v[82:83]
	v_max_f32_e32 v82, 0, v0
	v_max_f32_e32 v0, v84, v84
	v_max_f32_e32 v84, 0, v0
	v_max_f32_e32 v0, v89, v89
	v_max_f32_e32 v83, 0, v0
	v_max_f32_e32 v0, v85, v85
	v_max_f32_e32 v85, 0, v0
	v_max_f32_e32 v0, v78, v78
	v_max_f32_e32 v78, 0, v0
	v_max_f32_e32 v0, v74, v74
	v_pk_mul_f32 v[88:89], v[82:83], v[82:83]
	v_pk_mul_f32 v[92:93], v[84:85], v[84:85]
	v_max_f32_e32 v74, 0, v0
	v_max_f32_e32 v0, v79, v79
	v_cvt_pk_bf16_f32 v82, v86, v87
	v_cvt_pk_bf16_f32 v83, v88, v89
	v_cvt_pk_bf16_f32 v84, v90, v91
	v_cvt_pk_bf16_f32 v85, v92, v93
	v_max_f32_e32 v79, 0, v0
	v_max_f32_e32 v0, v75, v75
	v_permlane16_swap_b32_e32 v82, v84
	v_permlane16_swap_b32_e32 v83, v85
	v_max_f32_e32 v75, 0, v0
	v_max_f32_e32 v0, v80, v80
	flat_store_dwordx4 v[94:95], v[82:85] offset:32
	v_pk_mul_f32 v[78:79], v[78:79], v[78:79]
	s_nop 0
	v_pk_mul_f32 v[82:83], v[74:75], v[74:75]
	v_max_f32_e32 v74, 0, v0
	v_max_f32_e32 v0, v76, v76
	v_max_f32_e32 v76, 0, v0
	v_max_f32_e32 v0, v81, v81
	v_max_f32_e32 v75, 0, v0
	v_max_f32_e32 v0, v77, v77
	v_max_f32_e32 v77, 0, v0
	v_max_f32_e32 v0, v70, v70
	v_max_f32_e32 v70, 0, v0
	v_max_f32_e32 v0, v66, v66
	v_pk_mul_f32 v[80:81], v[74:75], v[74:75]
	v_pk_mul_f32 v[84:85], v[76:77], v[76:77]
	v_max_f32_e32 v66, 0, v0
	v_max_f32_e32 v0, v71, v71
	v_cvt_pk_bf16_f32 v74, v78, v79
	v_cvt_pk_bf16_f32 v75, v80, v81
	v_cvt_pk_bf16_f32 v76, v82, v83
	v_cvt_pk_bf16_f32 v77, v84, v85
	v_max_f32_e32 v71, 0, v0
	v_max_f32_e32 v0, v67, v67
	v_permlane16_swap_b32_e32 v74, v76
	v_permlane16_swap_b32_e32 v75, v77
	v_max_f32_e32 v67, 0, v0
	v_max_f32_e32 v0, v72, v72
	flat_store_dwordx4 v[94:95], v[74:77] offset:128
	v_pk_mul_f32 v[70:71], v[70:71], v[70:71]
	s_nop 0
	v_pk_mul_f32 v[74:75], v[66:67], v[66:67]
	v_max_f32_e32 v66, 0, v0
	v_max_f32_e32 v0, v68, v68
	v_max_f32_e32 v68, 0, v0
	v_max_f32_e32 v0, v73, v73
	v_max_f32_e32 v67, 0, v0
	v_max_f32_e32 v0, v69, v69
	v_max_f32_e32 v69, 0, v0
	v_pk_mul_f32 v[72:73], v[66:67], v[66:67]
	v_pk_mul_f32 v[76:77], v[68:69], v[68:69]
	v_cvt_pk_bf16_f32 v66, v70, v71
	v_cvt_pk_bf16_f32 v67, v72, v73
	v_cvt_pk_bf16_f32 v68, v74, v75
	v_cvt_pk_bf16_f32 v69, v76, v77
	s_nop 0
	v_permlane16_swap_b32_e32 v66, v68
	v_permlane16_swap_b32_e32 v67, v69
	flat_store_dwordx4 v[94:95], v[66:69] offset:160
	v_max_f32_e32 v0, v62, v62
	v_max_f32_e32 v62, 0, v0
	v_max_f32_e32 v0, v58, v58
	v_max_f32_e32 v58, 0, v0
	v_max_f32_e32 v0, v63, v63
	v_max_f32_e32 v63, 0, v0
	v_max_f32_e32 v0, v59, v59
	v_max_f32_e32 v59, 0, v0
	v_max_f32_e32 v0, v64, v64
	v_pk_mul_f32 v[68:69], v[58:59], v[58:59]
	v_max_f32_e32 v58, 0, v0
	v_max_f32_e32 v0, v60, v60
	v_max_f32_e32 v60, 0, v0
	v_max_f32_e32 v0, v65, v65
	v_max_f32_e32 v59, 0, v0
	v_max_f32_e32 v0, v61, v61
	v_add_u32_e32 v66, 64, v126
	v_max_f32_e32 v61, 0, v0
	v_max_f32_e32 v0, v54, v54
	v_ashrrev_i32_e32 v67, 31, v66
	v_max_f32_e32 v54, 0, v0
	v_max_f32_e32 v0, v50, v50
	v_and_b32_e32 v220, 1, v66
	v_lshrrev_b32_e32 v66, 1, v66
	v_mov_b32_e32 v67, 0
; DI unsigned pack2(float a, float b) { float2_t v = {a, b}; bf16x2_t r = __builtin_convertvector(v, bf16x2_t); return __builtin_bit_cast(unsigned, r); }
; DI void phase_mlp1(const Params& p, int l, int Mout, char* smem) {
;     ...
;   for (int it = 0;; ++it) {
;     int tm, tn;
;     if (!tile_map(it, ntm, 32, blk__, gridDim.x, tm, tn)) break;
;     ...
; #pragma unroll
;     for (int mi = 0; mi < 8; mi += 2) {
;       const int m = m0 + wr * 128 + (mi + (lq & 1)) * 16 + lr;
; #pragma unroll
;       for (int ni = 0; ni < 4; ++ni) {
;         const int n = n0 + wc * 64 + ni * 16 + (lq >> 1) * 8;
;         float va[4], vb[4];
; #pragma unroll
;         for (int j = 0; j < 4; ++j) { const float a = fmaxf(acc[mi][ni][j], 0.f); va[j] = a * a; const float b = fmaxf(acc[mi + 1][ni][j], 0.f); vb[j] = b * b; }
;         *(uint4*)(U + (size_t)m * DFF + n) = widen16(make_uint2(pack2(va[0], va[1]), pack2(va[2], va[3])), make_uint2(pack2(vb[0], vb[1]), pack2(vb[2], vb[3])));
;       }
;       __builtin_amdgcn_sched_barrier(0);
;     }
	v_lshlrev_b64 v[66:67], 14, v[66:67]
	v_lshl_or_b32 v66, v220, 6, v66
	v_pk_mul_f32 v[62:63], v[62:63], v[62:63]
	v_pk_mul_f32 v[64:65], v[58:59], v[58:59]
	v_pk_mul_f32 v[70:71], v[60:61], v[60:61]
	v_max_f32_e32 v50, 0, v0
	v_max_f32_e32 v0, v55, v55
	v_lshl_add_u64 v[66:67], s[60:61], 0, v[66:67]
	v_cvt_pk_bf16_f32 v58, v62, v63
	v_cvt_pk_bf16_f32 v59, v64, v65
	v_cvt_pk_bf16_f32 v60, v68, v69
	v_cvt_pk_bf16_f32 v61, v70, v71
	v_max_f32_e32 v55, 0, v0
	v_max_f32_e32 v0, v51, v51
	v_permlane16_swap_b32_e32 v58, v60
	v_permlane16_swap_b32_e32 v59, v61
	v_lshl_add_u64 v[62:63], v[66:67], 0, v[122:123]
	v_max_f32_e32 v51, 0, v0
	v_max_f32_e32 v0, v56, v56
	flat_store_dwordx4 v[62:63], v[58:61]
	v_pk_mul_f32 v[54:55], v[54:55], v[54:55]
	s_nop 0
	v_pk_mul_f32 v[58:59], v[50:51], v[50:51]
	v_max_f32_e32 v50, 0, v0
	v_max_f32_e32 v0, v52, v52
	v_max_f32_e32 v52, 0, v0
	v_max_f32_e32 v0, v57, v57
	v_max_f32_e32 v51, 0, v0
	v_max_f32_e32 v0, v53, v53
	v_max_f32_e32 v53, 0, v0
	v_max_f32_e32 v0, v46, v46
	v_max_f32_e32 v46, 0, v0
	v_max_f32_e32 v0, v42, v42
	v_pk_mul_f32 v[56:57], v[50:51], v[50:51]
	v_pk_mul_f32 v[60:61], v[52:53], v[52:53]
	v_max_f32_e32 v42, 0, v0
	v_max_f32_e32 v0, v47, v47
	v_cvt_pk_bf16_f32 v50, v54, v55
	v_cvt_pk_bf16_f32 v51, v56, v57
	v_cvt_pk_bf16_f32 v52, v58, v59
	v_cvt_pk_bf16_f32 v53, v60, v61
	v_max_f32_e32 v47, 0, v0
	v_max_f32_e32 v0, v43, v43
	v_permlane16_swap_b32_e32 v50, v52
	v_permlane16_swap_b32_e32 v51, v53
	v_max_f32_e32 v43, 0, v0
	v_max_f32_e32 v0, v48, v48
	flat_store_dwordx4 v[62:63], v[50:53] offset:32
	v_pk_mul_f32 v[46:47], v[46:47], v[46:47]
	s_nop 0
	v_pk_mul_f32 v[50:51], v[42:43], v[42:43]
	v_max_f32_e32 v42, 0, v0
	v_max_f32_e32 v0, v44, v44
	v_max_f32_e32 v44, 0, v0
	v_max_f32_e32 v0, v49, v49
	v_max_f32_e32 v43, 0, v0
	v_max_f32_e32 v0, v45, v45
	v_max_f32_e32 v45, 0, v0
	v_max_f32_e32 v0, v38, v38
	v_max_f32_e32 v38, 0, v0
	v_max_f32_e32 v0, v34, v34
	v_pk_mul_f32 v[48:49], v[42:43], v[42:43]
	v_pk_mul_f32 v[52:53], v[44:45], v[44:45]
	v_max_f32_e32 v34, 0, v0
	v_max_f32_e32 v0, v39, v39
	v_cvt_pk_bf16_f32 v42, v46, v47
	v_cvt_pk_bf16_f32 v43, v48, v49
	v_cvt_pk_bf16_f32 v44, v50, v51
	v_cvt_pk_bf16_f32 v45, v52, v53
	v_max_f32_e32 v39, 0, v0
	v_max_f32_e32 v0, v35, v35
	v_permlane16_swap_b32_e32 v42, v44
	v_permlane16_swap_b32_e32 v43, v45
	v_max_f32_e32 v35, 0, v0
	v_max_f32_e32 v0, v40, v40
	flat_store_dwordx4 v[62:63], v[42:45] offset:128
	v_pk_mul_f32 v[38:39], v[38:39], v[38:39]
	s_nop 0
	v_pk_mul_f32 v[42:43], v[34:35], v[34:35]
	v_max_f32_e32 v34, 0, v0
	v_max_f32_e32 v0, v36, v36
	v_max_f32_e32 v36, 0, v0
	v_max_f32_e32 v0, v41, v41
	v_max_f32_e32 v35, 0, v0
	v_max_f32_e32 v0, v37, v37
	v_max_f32_e32 v37, 0, v0
	v_pk_mul_f32 v[40:41], v[34:35], v[34:35]
	v_pk_mul_f32 v[44:45], v[36:37], v[36:37]
	v_cvt_pk_bf16_f32 v34, v38, v39
	v_cvt_pk_bf16_f32 v35, v40, v41
	v_cvt_pk_bf16_f32 v36, v42, v43
	v_cvt_pk_bf16_f32 v37, v44, v45
	s_nop 0
	v_permlane16_swap_b32_e32 v34, v36
	v_permlane16_swap_b32_e32 v35, v37
	flat_store_dwordx4 v[62:63], v[34:37] offset:160
	v_max_f32_e32 v0, v30, v30
	v_max_f32_e32 v30, 0, v0
	v_max_f32_e32 v0, v26, v26
	v_max_f32_e32 v26, 0, v0
	v_max_f32_e32 v0, v31, v31
	v_max_f32_e32 v31, 0, v0
	v_max_f32_e32 v0, v27, v27
	v_max_f32_e32 v27, 0, v0
	v_max_f32_e32 v0, v32, v32
	v_pk_mul_f32 v[36:37], v[26:27], v[26:27]
	v_max_f32_e32 v26, 0, v0
	v_max_f32_e32 v0, v28, v28
	v_max_f32_e32 v28, 0, v0
	v_max_f32_e32 v0, v33, v33
	v_max_f32_e32 v27, 0, v0
	v_max_f32_e32 v0, v29, v29
	v_add_u32_e32 v34, 0x60, v126
	v_max_f32_e32 v29, 0, v0
	v_max_f32_e32 v0, v22, v22
	v_ashrrev_i32_e32 v35, 31, v34
	v_max_f32_e32 v22, 0, v0
	v_max_f32_e32 v0, v18, v18
	v_and_b32_e32 v220, 1, v34
	v_lshrrev_b32_e32 v34, 1, v34
	v_mov_b32_e32 v35, 0
	v_lshlrev_b64 v[34:35], 14, v[34:35]
	v_lshl_or_b32 v34, v220, 6, v34
	v_pk_mul_f32 v[30:31], v[30:31], v[30:31]
	v_pk_mul_f32 v[32:33], v[26:27], v[26:27]
	v_pk_mul_f32 v[38:39], v[28:29], v[28:29]
	v_max_f32_e32 v18, 0, v0
	v_max_f32_e32 v0, v23, v23
	v_lshl_add_u64 v[34:35], s[60:61], 0, v[34:35]
	v_cvt_pk_bf16_f32 v26, v30, v31
	v_cvt_pk_bf16_f32 v27, v32, v33
	v_cvt_pk_bf16_f32 v28, v36, v37
	v_cvt_pk_bf16_f32 v29, v38, v39
	v_max_f32_e32 v23, 0, v0
	v_max_f32_e32 v0, v19, v19
	v_permlane16_swap_b32_e32 v26, v28
	v_permlane16_swap_b32_e32 v27, v29
	v_lshl_add_u64 v[30:31], v[34:35], 0, v[122:123]
	v_max_f32_e32 v19, 0, v0
	v_max_f32_e32 v0, v24, v24
	flat_store_dwordx4 v[30:31], v[26:29]
	v_pk_mul_f32 v[22:23], v[22:23], v[22:23]
	s_nop 0
	v_pk_mul_f32 v[26:27], v[18:19], v[18:19]
	v_max_f32_e32 v18, 0, v0
	v_max_f32_e32 v0, v20, v20
	v_max_f32_e32 v20, 0, v0
	v_max_f32_e32 v0, v25, v25
	v_max_f32_e32 v19, 0, v0
	v_max_f32_e32 v0, v21, v21
	v_max_f32_e32 v21, 0, v0
	v_max_f32_e32 v0, v14, v14
	v_max_f32_e32 v14, 0, v0
	v_max_f32_e32 v0, v10, v10
	v_pk_mul_f32 v[24:25], v[18:19], v[18:19]
	v_pk_mul_f32 v[28:29], v[20:21], v[20:21]
	v_max_f32_e32 v10, 0, v0
	v_max_f32_e32 v0, v15, v15
	v_cvt_pk_bf16_f32 v18, v22, v23
	v_cvt_pk_bf16_f32 v19, v24, v25
	v_cvt_pk_bf16_f32 v20, v26, v27
	v_cvt_pk_bf16_f32 v21, v28, v29
	v_max_f32_e32 v15, 0, v0
	v_max_f32_e32 v0, v11, v11
	v_permlane16_swap_b32_e32 v18, v20
	v_permlane16_swap_b32_e32 v19, v21
	v_max_f32_e32 v11, 0, v0
	v_max_f32_e32 v0, v16, v16
	flat_store_dwordx4 v[30:31], v[18:21] offset:32
	v_pk_mul_f32 v[14:15], v[14:15], v[14:15]
	s_nop 0
	v_pk_mul_f32 v[18:19], v[10:11], v[10:11]
	v_max_f32_e32 v10, 0, v0
	v_max_f32_e32 v0, v12, v12
	v_max_f32_e32 v12, 0, v0
	v_max_f32_e32 v0, v17, v17
	v_max_f32_e32 v11, 0, v0
	v_max_f32_e32 v0, v13, v13
	v_max_f32_e32 v13, 0, v0
	v_max_f32_e32 v0, v6, v6
	v_max_f32_e32 v6, 0, v0
	v_max_f32_e32 v0, v2, v2
	v_pk_mul_f32 v[16:17], v[10:11], v[10:11]
	v_pk_mul_f32 v[20:21], v[12:13], v[12:13]
	v_max_f32_e32 v2, 0, v0
	v_max_f32_e32 v0, v7, v7
	v_cvt_pk_bf16_f32 v10, v14, v15
	v_cvt_pk_bf16_f32 v11, v16, v17
	v_cvt_pk_bf16_f32 v12, v18, v19
	v_cvt_pk_bf16_f32 v13, v20, v21
	v_max_f32_e32 v7, 0, v0
	v_max_f32_e32 v0, v3, v3
	v_permlane16_swap_b32_e32 v10, v12
	v_permlane16_swap_b32_e32 v11, v13
	v_max_f32_e32 v3, 0, v0
	v_max_f32_e32 v0, v8, v8
	flat_store_dwordx4 v[30:31], v[10:13] offset:128
	v_pk_mul_f32 v[6:7], v[6:7], v[6:7]
	s_nop 0
	v_pk_mul_f32 v[10:11], v[2:3], v[2:3]
	v_max_f32_e32 v2, 0, v0
	v_max_f32_e32 v0, v4, v4
	v_max_f32_e32 v4, 0, v0
	v_max_f32_e32 v0, v9, v9
	v_max_f32_e32 v3, 0, v0
	v_max_f32_e32 v0, v5, v5
	v_max_f32_e32 v5, 0, v0
	v_pk_mul_f32 v[8:9], v[2:3], v[2:3]
	v_pk_mul_f32 v[12:13], v[4:5], v[4:5]
	v_cvt_pk_bf16_f32 v2, v6, v7
	v_cvt_pk_bf16_f32 v3, v8, v9
	v_cvt_pk_bf16_f32 v4, v10, v11
	v_cvt_pk_bf16_f32 v5, v12, v13
	s_nop 0
	v_permlane16_swap_b32_e32 v2, v4
	v_permlane16_swap_b32_e32 v3, v5
	flat_store_dwordx4 v[30:31], v[2:5] offset:160
	s_add_i32 s8, s8, 1
	s_mul_i32 s4, s8, s39
	s_add_i32 s9, s4, s6
	v_readlane_b32 s4, v253, 41
	s_cmp_ge_i32 s9, s4
	s_cbranch_scc0 .LBB0_441

; template <int MI, int NI>
; DI void gemm256(f32x4 (&acc)[MI][NI], const u16* __restrict__ A, int lda, const u16* __restrict__ Bt, int ldb, int K, int m0, int n0, char* smem) {
;     ...
;   for (int kt = 0; kt < nk; ++kt) {
;     if (kt + 1 < nk) asm volatile("s_waitcnt vmcnt(%0) lgkmcnt(0)" :: "n"(LPS) : "memory");
;     else asm volatile("s_waitcnt vmcnt(0) lgkmcnt(0)" ::: "memory");
;     __builtin_amdgcn_s_barrier();
;     __builtin_amdgcn_s_setprio(1);
;     const char* sb = smem + st * STAGE + foff;
;     bf16x8 af[MI], bfr[NI];
; #pragma unroll
;     for (int mi = 0; mi < MI; ++mi) af[mi] = *(const bf16x8*)(sb + (wr * MI + mi) * 1024);
; #pragma unroll
;     for (int ni = 0; ni < NI; ++ni) bfr[ni] = *(const bf16x8*)(sb + ABYTES + (wc * NI + ni) * 1024);
;     __builtin_amdgcn_sched_barrier(0x0);
;     if (kt + 2 < nk) { const int s2 = st >= 1 ? st - 1 : 2; G256_ISSUE(s2, (kt + 2) * 32); }
;     __builtin_amdgcn_s_setprio(0);
; #pragma unroll
;     for (int mi = 0; mi < MI; ++mi)
; #pragma unroll
;       for (int ni = 0; ni < NI; ++ni)
;         acc[mi][ni] = __builtin_amdgcn_mfma_f32_16x16x32_bf16(bfr[ni], af[mi], acc[mi][ni], 0, 0, 0);
;     st = st == 2 ? 0 : st + 1;
;   }
.Lpipe_wo:
	s_setprio 1
	v_add_u32_e32 v161, s12, v160
	ds_read_b128 v[156:159], v161 offset:4096
	ds_read_b128 v[164:167], v161 offset:5120
	ds_read_b128 v[168:171], v161 offset:6144
	ds_read_b128 v[172:175], v161 offset:7168
	s_add_i32 s14, s12, 0xffffa000
	s_cmp_eq_u32 s12, 0
	s_cselect_b32 s14, 0xc000, s14
	s_add_i32 s15, s14, s13
	s_add_i32 s14, s14, s4
	s_mov_b32 m0, s15
	s_waitcnt lgkmcnt(7)
	v_mfma_f32_16x16x32_bf16 v[126:129], v[176:179], v[140:143], v[126:129]
	global_load_lds_dwordx4 v[196:197], off
	v_mfma_f32_16x16x32_bf16 v[110:113], v[176:179], v[144:147], v[110:113]
	v_lshl_add_u64 v[196:197], v[196:197], 0, s[98:99]
	s_add_i32 m0, s15, 0x400
	v_mfma_f32_16x16x32_bf16 v[94:97], v[176:179], v[148:151], v[94:97]
	global_load_lds_dwordx4 v[198:199], off
	v_mfma_f32_16x16x32_bf16 v[78:81], v[176:179], v[152:155], v[78:81]
	v_lshl_add_u64 v[198:199], v[198:199], 0, s[98:99]
	s_add_i32 m0, s15, 0x800
	s_waitcnt lgkmcnt(6)
	v_mfma_f32_16x16x32_bf16 v[122:125], v[180:183], v[140:143], v[122:125]
	global_load_lds_dwordx4 v[200:201], off
	v_mfma_f32_16x16x32_bf16 v[106:109], v[180:183], v[144:147], v[106:109]
	v_lshl_add_u64 v[200:201], v[200:201], 0, s[98:99]
	s_add_i32 m0, s15, 0xc00
	v_mfma_f32_16x16x32_bf16 v[90:93], v[180:183], v[148:151], v[90:93]
	global_load_lds_dwordx4 v[202:203], off
	v_mfma_f32_16x16x32_bf16 v[74:77], v[180:183], v[152:155], v[74:77]
	v_lshl_add_u64 v[202:203], v[202:203], 0, s[98:99]
	s_mov_b32 m0, s14
	s_waitcnt lgkmcnt(5)
	v_mfma_f32_16x16x32_bf16 v[118:121], v[184:187], v[140:143], v[118:121]
	global_load_lds_dwordx4 v[204:205], off
	v_mfma_f32_16x16x32_bf16 v[102:105], v[184:187], v[144:147], v[102:105]
	v_lshl_add_u64 v[204:205], v[204:205], 0, 64
	s_add_i32 m0, s14, 0x400
	v_mfma_f32_16x16x32_bf16 v[86:89], v[184:187], v[148:151], v[86:89]
	global_load_lds_dwordx4 v[206:207], off
	v_mfma_f32_16x16x32_bf16 v[70:73], v[184:187], v[152:155], v[70:73]
	v_lshl_add_u64 v[206:207], v[206:207], 0, 64
	s_setprio 0
	s_waitcnt lgkmcnt(4)
	v_mfma_f32_16x16x32_bf16 v[114:117], v[188:191], v[140:143], v[114:117]
	v_mfma_f32_16x16x32_bf16 v[98:101], v[188:191], v[144:147], v[98:101]
	v_mfma_f32_16x16x32_bf16 v[82:85], v[188:191], v[148:151], v[82:85]
	v_mfma_f32_16x16x32_bf16 v[66:69], v[188:191], v[152:155], v[66:69]
	s_waitcnt vmcnt(6) lgkmcnt(0)
	s_barrier
	s_add_i32 s15, s12, 0x6000
	s_cmp_eq_u32 s12, 0xc000
	s_cselect_b32 s12, 0, s15
	v_add_u32_e32 v192, s12, v160
	v_add_u32_e32 v193, s12, v0
	v_mfma_f32_16x16x32_bf16 v[62:65], v[176:179], v[156:159], v[62:65]
	ds_read_b128 v[140:143], v192
	v_mfma_f32_16x16x32_bf16 v[46:49], v[176:179], v[164:167], v[46:49]
	ds_read_b128 v[144:147], v192 offset:1024
	v_mfma_f32_16x16x32_bf16 v[30:33], v[176:179], v[168:171], v[30:33]
	ds_read_b128 v[148:151], v192 offset:2048
	v_mfma_f32_16x16x32_bf16 v[14:17], v[176:179], v[172:175], v[14:17]
	ds_read_b128 v[152:155], v192 offset:3072
	ds_read_b128 v[176:179], v193 offset:16384
	v_mfma_f32_16x16x32_bf16 v[58:61], v[180:183], v[156:159], v[58:61]
	v_mfma_f32_16x16x32_bf16 v[42:45], v[180:183], v[164:167], v[42:45]
	v_mfma_f32_16x16x32_bf16 v[26:29], v[180:183], v[168:171], v[26:29]
	v_mfma_f32_16x16x32_bf16 v[10:13], v[180:183], v[172:175], v[10:13]
	ds_read_b128 v[180:183], v193 offset:17408
	v_mfma_f32_16x16x32_bf16 v[54:57], v[184:187], v[156:159], v[54:57]
	v_mfma_f32_16x16x32_bf16 v[38:41], v[184:187], v[164:167], v[38:41]
	v_mfma_f32_16x16x32_bf16 v[22:25], v[184:187], v[168:171], v[22:25]
	v_mfma_f32_16x16x32_bf16 v[6:9], v[184:187], v[172:175], v[6:9]
	ds_read_b128 v[184:187], v193 offset:18432
	v_mfma_f32_16x16x32_bf16 v[50:53], v[188:191], v[156:159], v[50:53]
	v_mfma_f32_16x16x32_bf16 v[34:37], v[188:191], v[164:167], v[34:37]
	v_mfma_f32_16x16x32_bf16 v[18:21], v[188:191], v[168:171], v[18:21]
	v_mfma_f32_16x16x32_bf16 v[2:5], v[188:191], v[172:175], v[2:5]
	ds_read_b128 v[188:191], v193 offset:19456
	s_sub_i32 s5, s5, 1
	s_cmp_lg_u32 s5, 0
	s_cbranch_scc1 .Lpipe_wo
	v_add_u32_e32 v161, s12, v160
	ds_read_b128 v[156:159], v161 offset:4096
	ds_read_b128 v[164:167], v161 offset:5120
	ds_read_b128 v[168:171], v161 offset:6144
	ds_read_b128 v[172:175], v161 offset:7168
	s_add_i32 s14, s12, 0xffffa000
	s_cmp_eq_u32 s12, 0
	s_cselect_b32 s14, 0xc000, s14
	s_add_i32 s15, s14, s13
	s_add_i32 s14, s14, s4
	s_mov_b32 m0, s15
	s_waitcnt lgkmcnt(7)
	v_mfma_f32_16x16x32_bf16 v[126:129], v[176:179], v[140:143], v[126:129]
	global_load_lds_dwordx4 v[196:197], off
	v_mfma_f32_16x16x32_bf16 v[110:113], v[176:179], v[144:147], v[110:113]
	v_lshl_add_u64 v[196:197], v[196:197], 0, s[98:99]
	s_add_i32 m0, s15, 0x400
	v_mfma_f32_16x16x32_bf16 v[94:97], v[176:179], v[148:151], v[94:97]
	global_load_lds_dwordx4 v[198:199], off
	v_mfma_f32_16x16x32_bf16 v[78:81], v[176:179], v[152:155], v[78:81]
	v_lshl_add_u64 v[198:199], v[198:199], 0, s[98:99]
	s_add_i32 m0, s15, 0x800
	s_waitcnt lgkmcnt(6)
	v_mfma_f32_16x16x32_bf16 v[122:125], v[180:183], v[140:143], v[122:125]
	global_load_lds_dwordx4 v[200:201], off
	v_mfma_f32_16x16x32_bf16 v[106:109], v[180:183], v[144:147], v[106:109]
	v_lshl_add_u64 v[200:201], v[200:201], 0, s[98:99]
	s_add_i32 m0, s15, 0xc00
	v_mfma_f32_16x16x32_bf16 v[90:93], v[180:183], v[148:151], v[90:93]
	global_load_lds_dwordx4 v[202:203], off
	v_mfma_f32_16x16x32_bf16 v[74:77], v[180:183], v[152:155], v[74:77]
	v_lshl_add_u64 v[202:203], v[202:203], 0, s[98:99]
	s_mov_b32 m0, s14
	s_waitcnt lgkmcnt(5)
; template <int MI, int NI>
; DI void gemm256(f32x4 (&acc)[MI][NI], const u16* __restrict__ A, int lda, const u16* __restrict__ Bt, int ldb, int K, int m0, int n0, char* smem) {
;     ...
;   for (int kt = 0; kt < nk; ++kt) {
;     if (kt + 1 < nk) asm volatile("s_waitcnt vmcnt(%0) lgkmcnt(0)" :: "n"(LPS) : "memory");
;     else asm volatile("s_waitcnt vmcnt(0) lgkmcnt(0)" ::: "memory");
;     __builtin_amdgcn_s_barrier();
;     __builtin_amdgcn_s_setprio(1);
;     const char* sb = smem + st * STAGE + foff;
;     bf16x8 af[MI], bfr[NI];
; #pragma unroll
;     for (int mi = 0; mi < MI; ++mi) af[mi] = *(const bf16x8*)(sb + (wr * MI + mi) * 1024);
; #pragma unroll
;     for (int ni = 0; ni < NI; ++ni) bfr[ni] = *(const bf16x8*)(sb + ABYTES + (wc * NI + ni) * 1024);
;     __builtin_amdgcn_sched_barrier(0x0);
;     if (kt + 2 < nk) { const int s2 = st >= 1 ? st - 1 : 2; G256_ISSUE(s2, (kt + 2) * 32); }
;     __builtin_amdgcn_s_setprio(0);
; #pragma unroll
;     for (int mi = 0; mi < MI; ++mi)
; #pragma unroll
;       for (int ni = 0; ni < NI; ++ni)
;         acc[mi][ni] = __builtin_amdgcn_mfma_f32_16x16x32_bf16(bfr[ni], af[mi], acc[mi][ni], 0, 0, 0);
;     st = st == 2 ? 0 : st + 1;
;   }
;   asm volatile("s_waitcnt lgkmcnt(0)" ::: "memory");
;   __builtin_amdgcn_s_barrier();
	v_mfma_f32_16x16x32_bf16 v[118:121], v[184:187], v[140:143], v[118:121]
	global_load_lds_dwordx4 v[204:205], off
	v_mfma_f32_16x16x32_bf16 v[102:105], v[184:187], v[144:147], v[102:105]
	v_lshl_add_u64 v[204:205], v[204:205], 0, 64
	s_add_i32 m0, s14, 0x400
	v_mfma_f32_16x16x32_bf16 v[86:89], v[184:187], v[148:151], v[86:89]
	global_load_lds_dwordx4 v[206:207], off
	v_mfma_f32_16x16x32_bf16 v[70:73], v[184:187], v[152:155], v[70:73]
	v_lshl_add_u64 v[206:207], v[206:207], 0, 64
	s_waitcnt lgkmcnt(4)
	v_mfma_f32_16x16x32_bf16 v[114:117], v[188:191], v[140:143], v[114:117]
	v_mfma_f32_16x16x32_bf16 v[98:101], v[188:191], v[144:147], v[98:101]
	v_mfma_f32_16x16x32_bf16 v[82:85], v[188:191], v[148:151], v[82:85]
	v_mfma_f32_16x16x32_bf16 v[66:69], v[188:191], v[152:155], v[66:69]
	s_waitcnt lgkmcnt(0)
	v_mfma_f32_16x16x32_bf16 v[62:65], v[176:179], v[156:159], v[62:65]
	v_mfma_f32_16x16x32_bf16 v[46:49], v[176:179], v[164:167], v[46:49]
	v_mfma_f32_16x16x32_bf16 v[30:33], v[176:179], v[168:171], v[30:33]
	v_mfma_f32_16x16x32_bf16 v[14:17], v[176:179], v[172:175], v[14:17]
	v_mfma_f32_16x16x32_bf16 v[58:61], v[180:183], v[156:159], v[58:61]
	v_mfma_f32_16x16x32_bf16 v[42:45], v[180:183], v[164:167], v[42:45]
	v_mfma_f32_16x16x32_bf16 v[26:29], v[180:183], v[168:171], v[26:29]
	v_mfma_f32_16x16x32_bf16 v[10:13], v[180:183], v[172:175], v[10:13]
	v_mfma_f32_16x16x32_bf16 v[54:57], v[184:187], v[156:159], v[54:57]
	v_mfma_f32_16x16x32_bf16 v[38:41], v[184:187], v[164:167], v[38:41]
	v_mfma_f32_16x16x32_bf16 v[22:25], v[184:187], v[168:171], v[22:25]
	v_mfma_f32_16x16x32_bf16 v[6:9], v[184:187], v[172:175], v[6:9]
	v_mfma_f32_16x16x32_bf16 v[50:53], v[188:191], v[156:159], v[50:53]
	v_mfma_f32_16x16x32_bf16 v[34:37], v[188:191], v[164:167], v[34:37]
	v_mfma_f32_16x16x32_bf16 v[18:21], v[188:191], v[168:171], v[18:21]
	v_mfma_f32_16x16x32_bf16 v[2:5], v[188:191], v[172:175], v[2:5]
	s_waitcnt vmcnt(6) lgkmcnt(0)
	s_barrier
	s_setprio 1
	v_add_u32_e32 v0, v137, v139
	ds_read_b128 v[130:133], v0
	ds_read_b128 v[140:143], v0 offset:1024
	ds_read_b128 v[144:147], v0 offset:2048
	ds_read_b128 v[148:151], v0 offset:3072
	ds_read_b128 v[152:155], v0 offset:4096
	ds_read_b128 v[156:159], v0 offset:5120
	ds_read_b128 v[164:167], v0 offset:6144
	ds_read_b128 v[168:171], v0 offset:7168
	v_add_u32_e32 v184, v137, v138
	ds_read_b128 v[136:139], v184 offset:16384
	ds_read_b128 v[172:175], v184 offset:17408
	ds_read_b128 v[176:179], v184 offset:18432
	ds_read_b128 v[180:183], v184 offset:19456
	v_bfe_u32 v188, v134, 6, 1
	s_setprio 0
	s_waitcnt vmcnt(0) lgkmcnt(0)
	s_waitcnt lgkmcnt(3)
	v_mfma_f32_16x16x32_bf16 v[126:129], v[136:139], v[130:133], v[126:129]
	v_ashrrev_i32_e32 v189, 7, v134
	v_and_b32_e32 v190, 15, v134
	v_bfe_u32 v191, v134, 4, 2
	s_waitcnt lgkmcnt(2)
	v_mfma_f32_16x16x32_bf16 v[122:125], v[172:175], v[130:133], v[122:125]
	s_barrier
	s_waitcnt lgkmcnt(1)
	v_mfma_f32_16x16x32_bf16 v[118:121], v[176:179], v[130:133], v[118:121]
	s_waitcnt lgkmcnt(0)
	v_mfma_f32_16x16x32_bf16 v[114:117], v[180:183], v[130:133], v[114:117]
	v_mfma_f32_16x16x32_bf16 v[110:113], v[136:139], v[140:143], v[110:113]
	v_mfma_f32_16x16x32_bf16 v[106:109], v[172:175], v[140:143], v[106:109]
	v_mfma_f32_16x16x32_bf16 v[102:105], v[176:179], v[140:143], v[102:105]
	v_mfma_f32_16x16x32_bf16 v[98:101], v[180:183], v[140:143], v[98:101]
	v_mfma_f32_16x16x32_bf16 v[94:97], v[136:139], v[144:147], v[94:97]
	v_mfma_f32_16x16x32_bf16 v[90:93], v[172:175], v[144:147], v[90:93]
	v_mfma_f32_16x16x32_bf16 v[86:89], v[176:179], v[144:147], v[86:89]
	v_mfma_f32_16x16x32_bf16 v[82:85], v[180:183], v[144:147], v[82:85]
	v_mfma_f32_16x16x32_bf16 v[78:81], v[136:139], v[148:151], v[78:81]
	v_mfma_f32_16x16x32_bf16 v[130:133], v[172:175], v[148:151], v[74:77]
	v_mfma_f32_16x16x32_bf16 v[70:73], v[176:179], v[148:151], v[70:73]
	v_mfma_f32_16x16x32_bf16 v[66:69], v[180:183], v[148:151], v[66:69]
	v_mfma_f32_16x16x32_bf16 v[62:65], v[136:139], v[152:155], v[62:65]
	v_mfma_f32_16x16x32_bf16 v[58:61], v[172:175], v[152:155], v[58:61]
	v_mfma_f32_16x16x32_bf16 v[54:57], v[176:179], v[152:155], v[54:57]
	v_mfma_f32_16x16x32_bf16 v[50:53], v[180:183], v[152:155], v[50:53]
	v_mfma_f32_16x16x32_bf16 v[46:49], v[136:139], v[156:159], v[46:49]
	v_mfma_f32_16x16x32_bf16 v[42:45], v[172:175], v[156:159], v[42:45]
	v_mfma_f32_16x16x32_bf16 v[38:41], v[176:179], v[156:159], v[38:41]
	v_mfma_f32_16x16x32_bf16 v[34:37], v[180:183], v[156:159], v[34:37]
	v_mfma_f32_16x16x32_bf16 v[30:33], v[136:139], v[164:167], v[30:33]
	v_mfma_f32_16x16x32_bf16 v[26:29], v[172:175], v[164:167], v[26:29]
	v_mfma_f32_16x16x32_bf16 v[22:25], v[176:179], v[164:167], v[22:25]
	v_mfma_f32_16x16x32_bf16 v[18:21], v[180:183], v[164:167], v[18:21]
	v_mfma_f32_16x16x32_bf16 v[14:17], v[136:139], v[168:171], v[14:17]
	v_mfma_f32_16x16x32_bf16 v[10:13], v[172:175], v[168:171], v[10:13]
	v_mfma_f32_16x16x32_bf16 v[6:9], v[176:179], v[168:171], v[6:9]
	v_mfma_f32_16x16x32_bf16 v[134:137], v[180:183], v[168:171], v[2:5]
	s_setprio 1
	s_nop 1
	ds_read_b128 v[2:5], v0 offset:24576
	ds_read_b128 v[74:77], v0 offset:25600
	ds_read_b128 v[138:141], v0 offset:26624
	ds_read_b128 v[142:145], v0 offset:27648
	ds_read_b128 v[146:149], v0 offset:28672
	ds_read_b128 v[150:153], v0 offset:29696
	ds_read_b128 v[154:157], v0 offset:30720
	ds_read_b128 v[158:161], v0 offset:31744
	ds_read_b128 v[164:167], v184 offset:40960
	ds_read_b128 v[168:171], v184 offset:41984
	ds_read_b128 v[172:175], v184 offset:43008
	ds_read_b128 v[176:179], v184 offset:44032
	s_setprio 0
	s_waitcnt lgkmcnt(0)
	s_barrier
; template <int MI, int NI>
; DI void gemm256(f32x4 (&acc)[MI][NI], const u16* __restrict__ A, int lda, const u16* __restrict__ Bt, int ldb, int K, int m0, int n0, char* smem) {
;     ...
; #pragma unroll
;     for (int mi = 0; mi < MI; ++mi)
; #pragma unroll
;       for (int ni = 0; ni < NI; ++ni)
;         acc[mi][ni] = __builtin_amdgcn_mfma_f32_16x16x32_bf16(bfr[ni], af[mi], acc[mi][ni], 0, 0, 0);
; template <int MI, int NI>
; DI void resid_tile(const u16* A, int K, const u16* Bt, const float* gate, const float* xl_in, const float* xc_in, float* xl_out, float* xc_out,
;                    int m0, int n0, char* smem) {
;     ...
; #pragma unroll
;   for (int mi = 0; mi < MI; ++mi) {
;     const int m = m0 + wr * 16 * MI + mi * 16 + lr;
;     const int b9 = m < NTL ? m >> 12 : 8;
;     const float* xi = xrow(xl_in, xc_in, m);
;     float* xo = m < NTL ? xl_out + (size_t)m * D : xc_out + (size_t)(m - NTL) * D;
; #pragma unroll
;     for (int ni = 0; ni < NI; ++ni) {
;       const int n = n0 + wc * 16 * NI + ni * 16 + lq * 4;
;       const float4 g = *(const float4*)(gate + (size_t)b9 * 6144 + n);
;       const float4 xv = *(const float4*)(xi + n);
;       float4 ov;
;       ov.x = xv.x + g.x * acc[mi][ni][0]; ov.y = xv.y + g.y * acc[mi][ni][1]; ov.z = xv.z + g.z * acc[mi][ni][2]; ov.w = xv.w + g.w * acc[mi][ni][3];
;       *(float4*)(xo + n) = ov;
;     }
	v_readlane_b32 s4, v253, 55
	v_lshlrev_b32_e32 v0, 7, v189
	s_waitcnt lgkmcnt(3)
	v_mfma_f32_16x16x32_bf16 v[126:129], v[164:167], v[2:5], v[126:129]
	s_waitcnt lgkmcnt(2)
	v_mfma_f32_16x16x32_bf16 v[122:125], v[168:171], v[2:5], v[122:125]
	s_waitcnt lgkmcnt(1)
	v_mfma_f32_16x16x32_bf16 v[180:183], v[172:175], v[2:5], v[118:121]
	s_waitcnt lgkmcnt(0)
	v_mfma_f32_16x16x32_bf16 v[184:187], v[176:179], v[2:5], v[114:117]
	v_lshlrev_b32_e32 v2, 2, v191
	v_mov_b32_e32 v118, s4
	v_readlane_b32 s4, v253, 53
	v_add3_u32 v116, v190, s10, v0
	v_lshlrev_b32_e32 v0, 6, v188
	v_add3_u32 v2, v2, s11, v0
	v_min_i32_e32 v0, 0x8000, v116
	v_mov_b32_e32 v119, s4
	v_readlane_b32 s4, v253, 56
	v_mfma_f32_16x16x32_bf16 v[110:113], v[164:167], v[74:77], v[110:113]
	v_ashrrev_i32_e32 v117, 31, v116
	v_cmp_gt_i32_e32 vcc, s58, v116
	v_mov_b32_e32 v120, s4
	v_mfma_f32_16x16x32_bf16 v[106:109], v[168:171], v[74:77], v[106:109]
	v_readlane_b32 s4, v253, 54
	v_cndmask_b32_e32 v5, 0, v117, vcc
	v_cndmask_b32_e32 v115, v118, v119, vcc
	v_mfma_f32_16x16x32_bf16 v[102:105], v[172:175], v[74:77], v[102:105]
	v_mov_b32_e32 v121, s4
	v_cndmask_b32_e32 v114, v120, v121, vcc
	v_readlane_b32 s4, v253, 51
	v_mfma_f32_16x16x32_bf16 v[98:101], v[176:179], v[74:77], v[98:101]
	v_ashrrev_i32_e32 v3, 31, v2
	v_readlane_b32 s5, v253, 52
	v_mfma_f32_16x16x32_bf16 v[74:77], v[164:167], v[142:145], v[78:81]
	v_mfma_f32_16x16x32_bf16 v[78:81], v[168:171], v[142:145], v[130:133]
	s_nop 2
	v_ashrrev_i32_e32 v130, 12, v0
	v_add_u32_e32 v0, 0xffff8000, v116
	v_cndmask_b32_e32 v4, v0, v116, vcc
	v_lshlrev_b64 v[4:5], 12, v[4:5]
	v_lshl_add_u64 v[4:5], v[114:115], 0, v[4:5]
	v_mul_hi_i32_i24_e32 v115, 0x6000, v130
	v_mul_i32_i24_e32 v114, 0x6000, v130
	v_lshl_add_u64 v[130:131], s[4:5], 0, v[114:115]
	v_lshlrev_b64 v[114:115], 2, v[2:3]
	v_mfma_f32_16x16x32_bf16 v[94:97], v[164:167], v[138:141], v[94:97]
	v_mfma_f32_16x16x32_bf16 v[90:93], v[168:171], v[138:141], v[90:93]
	v_mfma_f32_16x16x32_bf16 v[86:89], v[172:175], v[138:141], v[86:89]
	v_mfma_f32_16x16x32_bf16 v[82:85], v[176:179], v[138:141], v[82:85]
	v_lshl_add_u64 v[138:139], v[130:131], 0, v[114:115]
	v_lshl_add_u64 v[140:141], v[4:5], 0, v[114:115]
	flat_load_dwordx4 v[2:5], v[138:139]
	flat_load_dwordx4 v[130:133], v[140:141]
	v_mfma_f32_16x16x32_bf16 v[70:73], v[172:175], v[142:145], v[70:73]
	s_waitcnt vmcnt(0) lgkmcnt(0)
	v_pk_fma_f32 v[2:3], v[126:127], v[2:3], v[130:131]
	v_mfma_f32_16x16x32_bf16 v[66:69], v[176:179], v[142:145], v[66:69]
	v_lshlrev_b64 v[142:143], 12, v[116:117]
	v_lshlrev_b64 v[144:145], 12, v[0:1]
	v_lshl_add_u64 v[142:143], s[48:49], 0, v[142:143]
	v_lshl_add_u64 v[144:145], s[94:95], 0, v[144:145]
	v_cndmask_b32_e32 v143, v145, v143, vcc
	v_cndmask_b32_e32 v142, v144, v142, vcc
	v_lshl_add_u64 v[142:143], v[142:143], 0, v[114:115]
	v_pk_fma_f32 v[4:5], v[128:129], v[4:5], v[132:133]
	flat_store_dwordx4 v[142:143], v[2:5]
	flat_load_dwordx4 v[126:129], v[138:139] offset:64
	flat_load_dwordx4 v[130:133], v[140:141] offset:64
	v_mfma_f32_16x16x32_bf16 v[2:5], v[168:171], v[158:161], v[10:13]
	v_mfma_f32_16x16x32_bf16 v[62:65], v[164:167], v[146:149], v[62:65]
	s_waitcnt vmcnt(0) lgkmcnt(0)
	s_nop 0
	v_pk_fma_f32 v[10:11], v[122:123], v[126:127], v[130:131]
	v_pk_fma_f32 v[12:13], v[124:125], v[128:129], v[132:133]
	flat_store_dwordx4 v[142:143], v[10:13] offset:64
	flat_load_dwordx4 v[10:13], v[138:139] offset:128
	s_nop 0
	flat_load_dwordx4 v[122:125], v[140:141] offset:128
	v_mfma_f32_16x16x32_bf16 v[58:61], v[168:171], v[146:149], v[58:61]
	s_waitcnt vmcnt(0) lgkmcnt(0)
	v_pk_fma_f32 v[10:11], v[180:181], v[10:11], v[122:123]
	v_pk_fma_f32 v[12:13], v[182:183], v[12:13], v[124:125]
	flat_store_dwordx4 v[142:143], v[10:13] offset:128
	flat_load_dwordx4 v[122:125], v[138:139] offset:192
	flat_load_dwordx4 v[126:129], v[140:141] offset:192
	v_mfma_f32_16x16x32_bf16 v[54:57], v[172:175], v[146:149], v[54:57]
	s_waitcnt vmcnt(0) lgkmcnt(0)
	v_pk_fma_f32 v[122:123], v[184:185], v[122:123], v[126:127]
	v_pk_fma_f32 v[124:125], v[186:187], v[124:125], v[128:129]
	v_mfma_f32_16x16x32_bf16 v[50:53], v[176:179], v[146:149], v[50:53]
	flat_store_dwordx4 v[142:143], v[122:125] offset:192
	v_mfma_f32_16x16x32_bf16 v[46:49], v[164:167], v[150:153], v[46:49]
	v_mfma_f32_16x16x32_bf16 v[42:45], v[168:171], v[150:153], v[42:45]
	v_mfma_f32_16x16x32_bf16 v[38:41], v[172:175], v[150:153], v[38:41]
	v_mfma_f32_16x16x32_bf16 v[34:37], v[176:179], v[150:153], v[34:37]
	v_mfma_f32_16x16x32_bf16 v[30:33], v[164:167], v[154:157], v[30:33]
	v_mfma_f32_16x16x32_bf16 v[26:29], v[168:171], v[154:157], v[26:29]
	v_mfma_f32_16x16x32_bf16 v[22:25], v[172:175], v[154:157], v[22:25]
	v_mfma_f32_16x16x32_bf16 v[18:21], v[176:179], v[154:157], v[18:21]
	v_mfma_f32_16x16x32_bf16 v[14:17], v[164:167], v[158:161], v[14:17]
	v_mfma_f32_16x16x32_bf16 v[6:9], v[172:175], v[158:161], v[6:9]
	v_mfma_f32_16x16x32_bf16 v[10:13], v[176:179], v[158:161], v[134:137]
	v_add_u32_e32 v122, 16, v116
	v_min_i32_e32 v0, 0x8000, v122
	v_cmp_gt_i32_e32 vcc, s58, v122
	v_ashrrev_i32_e32 v117, 12, v0
	v_add_u32_e32 v0, 0xffff8010, v116
	v_ashrrev_i32_e32 v123, 31, v122
	v_cndmask_b32_e32 v125, 0, v123, vcc
	v_cndmask_b32_e32 v124, v0, v122, vcc
	v_cndmask_b32_e32 v127, v118, v119, vcc
	v_cndmask_b32_e32 v126, v120, v121, vcc
	v_lshlrev_b64 v[124:125], 12, v[124:125]
	v_lshl_add_u64 v[124:125], v[126:127], 0, v[124:125]
	v_lshlrev_b64 v[122:123], 12, v[122:123]
	v_lshlrev_b64 v[126:127], 12, v[0:1]
	v_lshl_add_u64 v[122:123], s[48:49], 0, v[122:123]
	v_lshl_add_u64 v[126:127], s[94:95], 0, v[126:127]
	v_cndmask_b32_e32 v123, v127, v123, vcc
	v_cndmask_b32_e32 v122, v126, v122, vcc
	v_mul_hi_i32_i24_e32 v127, 0x6000, v117
	v_mul_i32_i24_e32 v126, 0x6000, v117
	v_lshl_add_u64 v[126:127], s[4:5], 0, v[126:127]
	v_lshl_add_u64 v[130:131], v[126:127], 0, v[114:115]
	v_lshl_add_u64 v[132:133], v[124:125], 0, v[114:115]
	v_lshl_add_u64 v[134:135], v[122:123], 0, v[114:115]
	global_load_dwordx4 v[156:159], v[130:131], off
	global_load_dwordx4 v[164:167], v[130:131], off offset:64
	global_load_dwordx4 v[168:171], v[130:131], off offset:128
	global_load_dwordx4 v[172:175], v[130:131], off offset:192
	global_load_dwordx4 v[140:143], v[132:133], off
	global_load_dwordx4 v[144:147], v[132:133], off offset:64
	global_load_dwordx4 v[148:151], v[132:133], off offset:128
	global_load_dwordx4 v[152:155], v[132:133], off offset:192
	v_mov_b32_e32 v216, 0x10000
	v_mov_b32_e32 v217, 0
	v_lshl_add_u64 v[212:213], v[132:133], 0, v[216:217]
	v_lshl_add_u64 v[214:215], v[134:135], 0, v[216:217]
	global_load_dwordx4 v[176:179], v[212:213], off
	global_load_dwordx4 v[180:183], v[212:213], off offset:64
	global_load_dwordx4 v[184:187], v[212:213], off offset:128
	global_load_dwordx4 v[188:191], v[212:213], off offset:192
	v_lshl_add_u64 v[212:213], v[212:213], 0, v[216:217]
	s_waitcnt vmcnt(4)
; template <int MI, int NI>
; DI void resid_tile(const u16* A, int K, const u16* Bt, const float* gate, const float* xl_in, const float* xc_in, float* xl_out, float* xc_out,
;                    int m0, int n0, char* smem) {
;     ...
; #pragma unroll
;   for (int mi = 0; mi < MI; ++mi) {
;     const int m = m0 + wr * 16 * MI + mi * 16 + lr;
;     const int b9 = m < NTL ? m >> 12 : 8;
;     const float* xi = xrow(xl_in, xc_in, m);
;     float* xo = m < NTL ? xl_out + (size_t)m * D : xc_out + (size_t)(m - NTL) * D;
; #pragma unroll
;     for (int ni = 0; ni < NI; ++ni) {
;       const int n = n0 + wc * 16 * NI + ni * 16 + lq * 4;
;       const float4 g = *(const float4*)(gate + (size_t)b9 * 6144 + n);
;       const float4 xv = *(const float4*)(xi + n);
;       float4 ov;
;       ov.x = xv.x + g.x * acc[mi][ni][0]; ov.y = xv.y + g.y * acc[mi][ni][1]; ov.z = xv.z + g.z * acc[mi][ni][2]; ov.w = xv.w + g.w * acc[mi][ni][3];
;       *(float4*)(xo + n) = ov;
;     }
; DI void phase_resid(const Params& p, const u16* A, int K, const u16* Bt, const float* gate  ,
;                     const float* xl_in, const float* xc_in, float* xl_out, float* xc_out, int Mout, char* smem) {
;     ...
;   for (int it = 0;; ++it) {
;     int tm, tn;
;     if (!tile_map(it, NTL / 256, 8, blk__, gridDim.x, tm, tn)) break;
;     resid_tile<8, 4>(A, K, Bt, gate, xl_in, xc_in, xl_out, xc_out, tm * 256, tn * 128, smem);
;   }
	v_pk_fma_f32 v[110:111], v[110:111], v[156:157], v[140:141]
	v_pk_fma_f32 v[112:113], v[112:113], v[158:159], v[142:143]
	v_pk_fma_f32 v[106:107], v[106:107], v[164:165], v[144:145]
	v_pk_fma_f32 v[108:109], v[108:109], v[166:167], v[146:147]
	v_pk_fma_f32 v[102:103], v[102:103], v[168:169], v[148:149]
	v_pk_fma_f32 v[104:105], v[104:105], v[170:171], v[150:151]
	v_pk_fma_f32 v[98:99], v[98:99], v[172:173], v[152:153]
	v_pk_fma_f32 v[100:101], v[100:101], v[174:175], v[154:155]
	global_store_dwordx4 v[134:135], v[110:113], off
	global_store_dwordx4 v[134:135], v[106:109], off offset:64
	global_store_dwordx4 v[134:135], v[102:105], off offset:128
	global_store_dwordx4 v[134:135], v[98:101], off offset:192
	global_load_dwordx4 v[140:143], v[212:213], off
	global_load_dwordx4 v[144:147], v[212:213], off offset:64
	global_load_dwordx4 v[148:151], v[212:213], off offset:128
	global_load_dwordx4 v[152:155], v[212:213], off offset:192
	v_lshl_add_u64 v[212:213], v[212:213], 0, v[216:217]
	s_waitcnt vmcnt(8)
	v_pk_fma_f32 v[94:95], v[94:95], v[156:157], v[176:177]
	v_pk_fma_f32 v[96:97], v[96:97], v[158:159], v[178:179]
	v_pk_fma_f32 v[90:91], v[90:91], v[164:165], v[180:181]
	v_pk_fma_f32 v[92:93], v[92:93], v[166:167], v[182:183]
	v_pk_fma_f32 v[86:87], v[86:87], v[168:169], v[184:185]
	v_pk_fma_f32 v[88:89], v[88:89], v[170:171], v[186:187]
	v_pk_fma_f32 v[82:83], v[82:83], v[172:173], v[188:189]
	v_pk_fma_f32 v[84:85], v[84:85], v[174:175], v[190:191]
	global_store_dwordx4 v[214:215], v[94:97], off
	global_store_dwordx4 v[214:215], v[90:93], off offset:64
	global_store_dwordx4 v[214:215], v[86:89], off offset:128
	global_store_dwordx4 v[214:215], v[82:85], off offset:192
	v_lshl_add_u64 v[214:215], v[214:215], 0, v[216:217]
	global_load_dwordx4 v[176:179], v[212:213], off
	global_load_dwordx4 v[180:183], v[212:213], off offset:64
	global_load_dwordx4 v[184:187], v[212:213], off offset:128
	global_load_dwordx4 v[188:191], v[212:213], off offset:192
	v_lshl_add_u64 v[212:213], v[212:213], 0, v[216:217]
	s_waitcnt vmcnt(8)
	v_pk_fma_f32 v[74:75], v[74:75], v[156:157], v[140:141]
	v_pk_fma_f32 v[76:77], v[76:77], v[158:159], v[142:143]
	v_pk_fma_f32 v[78:79], v[78:79], v[164:165], v[144:145]
	v_pk_fma_f32 v[80:81], v[80:81], v[166:167], v[146:147]
	v_pk_fma_f32 v[70:71], v[70:71], v[168:169], v[148:149]
	v_pk_fma_f32 v[72:73], v[72:73], v[170:171], v[150:151]
	v_pk_fma_f32 v[66:67], v[66:67], v[172:173], v[152:153]
	v_pk_fma_f32 v[68:69], v[68:69], v[174:175], v[154:155]
	global_store_dwordx4 v[214:215], v[74:77], off
	global_store_dwordx4 v[214:215], v[78:81], off offset:64
	global_store_dwordx4 v[214:215], v[70:73], off offset:128
	global_store_dwordx4 v[214:215], v[66:69], off offset:192
	v_lshl_add_u64 v[214:215], v[214:215], 0, v[216:217]
	global_load_dwordx4 v[140:143], v[212:213], off
	global_load_dwordx4 v[144:147], v[212:213], off offset:64
	global_load_dwordx4 v[148:151], v[212:213], off offset:128
	global_load_dwordx4 v[152:155], v[212:213], off offset:192
	v_lshl_add_u64 v[212:213], v[212:213], 0, v[216:217]
	s_waitcnt vmcnt(8)
	v_pk_fma_f32 v[62:63], v[62:63], v[156:157], v[176:177]
	v_pk_fma_f32 v[64:65], v[64:65], v[158:159], v[178:179]
	v_pk_fma_f32 v[58:59], v[58:59], v[164:165], v[180:181]
	v_pk_fma_f32 v[60:61], v[60:61], v[166:167], v[182:183]
	v_pk_fma_f32 v[54:55], v[54:55], v[168:169], v[184:185]
	v_pk_fma_f32 v[56:57], v[56:57], v[170:171], v[186:187]
	v_pk_fma_f32 v[50:51], v[50:51], v[172:173], v[188:189]
	v_pk_fma_f32 v[52:53], v[52:53], v[174:175], v[190:191]
	global_store_dwordx4 v[214:215], v[62:65], off
	global_store_dwordx4 v[214:215], v[58:61], off offset:64
	global_store_dwordx4 v[214:215], v[54:57], off offset:128
	global_store_dwordx4 v[214:215], v[50:53], off offset:192
	v_lshl_add_u64 v[214:215], v[214:215], 0, v[216:217]
	global_load_dwordx4 v[176:179], v[212:213], off
	global_load_dwordx4 v[180:183], v[212:213], off offset:64
	global_load_dwordx4 v[184:187], v[212:213], off offset:128
	global_load_dwordx4 v[188:191], v[212:213], off offset:192
	v_lshl_add_u64 v[212:213], v[212:213], 0, v[216:217]
	s_waitcnt vmcnt(8)
	v_pk_fma_f32 v[46:47], v[46:47], v[156:157], v[140:141]
	v_pk_fma_f32 v[48:49], v[48:49], v[158:159], v[142:143]
	v_pk_fma_f32 v[42:43], v[42:43], v[164:165], v[144:145]
	v_pk_fma_f32 v[44:45], v[44:45], v[166:167], v[146:147]
	v_pk_fma_f32 v[38:39], v[38:39], v[168:169], v[148:149]
	v_pk_fma_f32 v[40:41], v[40:41], v[170:171], v[150:151]
	v_pk_fma_f32 v[34:35], v[34:35], v[172:173], v[152:153]
	v_pk_fma_f32 v[36:37], v[36:37], v[174:175], v[154:155]
	global_store_dwordx4 v[214:215], v[46:49], off
	global_store_dwordx4 v[214:215], v[42:45], off offset:64
	global_store_dwordx4 v[214:215], v[38:41], off offset:128
	global_store_dwordx4 v[214:215], v[34:37], off offset:192
	v_lshl_add_u64 v[214:215], v[214:215], 0, v[216:217]
	global_load_dwordx4 v[140:143], v[212:213], off
	global_load_dwordx4 v[144:147], v[212:213], off offset:64
	global_load_dwordx4 v[148:151], v[212:213], off offset:128
	global_load_dwordx4 v[152:155], v[212:213], off offset:192
	s_waitcnt vmcnt(8)
	v_pk_fma_f32 v[30:31], v[30:31], v[156:157], v[176:177]
	v_pk_fma_f32 v[32:33], v[32:33], v[158:159], v[178:179]
	v_pk_fma_f32 v[26:27], v[26:27], v[164:165], v[180:181]
	v_pk_fma_f32 v[28:29], v[28:29], v[166:167], v[182:183]
	v_pk_fma_f32 v[22:23], v[22:23], v[168:169], v[184:185]
	v_pk_fma_f32 v[24:25], v[24:25], v[170:171], v[186:187]
	v_pk_fma_f32 v[18:19], v[18:19], v[172:173], v[188:189]
	v_pk_fma_f32 v[20:21], v[20:21], v[174:175], v[190:191]
	global_store_dwordx4 v[214:215], v[30:33], off
	global_store_dwordx4 v[214:215], v[26:29], off offset:64
	global_store_dwordx4 v[214:215], v[22:25], off offset:128
	global_store_dwordx4 v[214:215], v[18:21], off offset:192
	v_lshl_add_u64 v[214:215], v[214:215], 0, v[216:217]
	s_waitcnt vmcnt(4)
	v_pk_fma_f32 v[14:15], v[14:15], v[156:157], v[140:141]
	v_pk_fma_f32 v[16:17], v[16:17], v[158:159], v[142:143]
	v_pk_fma_f32 v[2:3], v[2:3], v[164:165], v[144:145]
	v_pk_fma_f32 v[4:5], v[4:5], v[166:167], v[146:147]
	v_pk_fma_f32 v[6:7], v[6:7], v[168:169], v[148:149]
	v_pk_fma_f32 v[8:9], v[8:9], v[170:171], v[150:151]
	v_pk_fma_f32 v[10:11], v[10:11], v[172:173], v[152:153]
	v_pk_fma_f32 v[12:13], v[12:13], v[174:175], v[154:155]
	global_store_dwordx4 v[214:215], v[14:17], off
	global_store_dwordx4 v[214:215], v[2:5], off offset:64
	global_store_dwordx4 v[214:215], v[6:9], off offset:128
	global_store_dwordx4 v[214:215], v[10:13], off offset:192
	s_add_i32 s9, s9, 1
	s_mul_i32 s4, s9, s39
	s_add_i32 s4, s4, s7
	s_cmpk_gt_i32 s4, 0x7f
	s_cbranch_scc0 .LBB0_461

; template <int MI, int NI>
; DI void gemm256(f32x4 (&acc)[MI][NI], const u16* __restrict__ A, int lda, const u16* __restrict__ Bt, int ldb, int K, int m0, int n0, char* smem) {
;     ...
;   for (int kt = 0; kt < nk; ++kt) {
;     if (kt + 1 < nk) asm volatile("s_waitcnt vmcnt(%0) lgkmcnt(0)" :: "n"(LPS) : "memory");
;     else asm volatile("s_waitcnt vmcnt(0) lgkmcnt(0)" ::: "memory");
;     __builtin_amdgcn_s_barrier();
;     __builtin_amdgcn_s_setprio(1);
;     const char* sb = smem + st * STAGE + foff;
;     bf16x8 af[MI], bfr[NI];
; #pragma unroll
;     for (int mi = 0; mi < MI; ++mi) af[mi] = *(const bf16x8*)(sb + (wr * MI + mi) * 1024);
; #pragma unroll
;     for (int ni = 0; ni < NI; ++ni) bfr[ni] = *(const bf16x8*)(sb + ABYTES + (wc * NI + ni) * 1024);
;     __builtin_amdgcn_sched_barrier(0x0);
;     if (kt + 2 < nk) { const int s2 = st >= 1 ? st - 1 : 2; G256_ISSUE(s2, (kt + 2) * 32); }
;     __builtin_amdgcn_s_setprio(0);
; #pragma unroll
;     for (int mi = 0; mi < MI; ++mi)
; #pragma unroll
;       for (int ni = 0; ni < NI; ++ni)
;         acc[mi][ni] = __builtin_amdgcn_mfma_f32_16x16x32_bf16(bfr[ni], af[mi], acc[mi][ni], 0, 0, 0);
;     st = st == 2 ? 0 : st + 1;
;   }
.Lpipe_zgemm:
	s_setprio 1
	v_add_u32_e32 v160, s6, v143
	ds_read_b128 v[164:167], v160 offset:4096
	ds_read_b128 v[168:171], v160 offset:5120
	ds_read_b128 v[172:175], v160 offset:6144
	ds_read_b128 v[176:179], v160 offset:7168
	s_add_i32 s8, s6, 0xffffa000
	s_cmp_eq_u32 s6, 0
	s_cselect_b32 s8, 0xc000, s8
	s_add_i32 s9, s8, s7
	s_add_i32 s8, s8, s0
	s_mov_b32 m0, s9
	s_waitcnt lgkmcnt(7)
	v_mfma_f32_16x16x32_bf16 v[126:129], v[180:183], v[144:147], v[126:129]
	global_load_lds_dwordx4 v[198:199], off
	v_mfma_f32_16x16x32_bf16 v[110:113], v[180:183], v[148:151], v[110:113]
	v_lshl_add_u64 v[198:199], v[198:199], 0, s[98:99]
	s_add_i32 m0, s9, 0x400
	v_mfma_f32_16x16x32_bf16 v[94:97], v[180:183], v[152:155], v[94:97]
	global_load_lds_dwordx4 v[200:201], off
	v_mfma_f32_16x16x32_bf16 v[78:81], v[180:183], v[156:159], v[78:81]
	v_lshl_add_u64 v[200:201], v[200:201], 0, s[98:99]
	s_add_i32 m0, s9, 0x800
	s_waitcnt lgkmcnt(6)
	v_mfma_f32_16x16x32_bf16 v[122:125], v[184:187], v[144:147], v[122:125]
	global_load_lds_dwordx4 v[202:203], off
	v_mfma_f32_16x16x32_bf16 v[106:109], v[184:187], v[148:151], v[106:109]
	v_lshl_add_u64 v[202:203], v[202:203], 0, s[98:99]
	s_add_i32 m0, s9, 0xc00
	v_mfma_f32_16x16x32_bf16 v[90:93], v[184:187], v[152:155], v[90:93]
	global_load_lds_dwordx4 v[204:205], off
	v_mfma_f32_16x16x32_bf16 v[74:77], v[184:187], v[156:159], v[74:77]
	v_lshl_add_u64 v[204:205], v[204:205], 0, s[98:99]
	s_mov_b32 m0, s8
	s_waitcnt lgkmcnt(5)
	v_mfma_f32_16x16x32_bf16 v[118:121], v[188:191], v[144:147], v[118:121]
	global_load_lds_dwordx4 v[206:207], off
	v_mfma_f32_16x16x32_bf16 v[102:105], v[188:191], v[148:151], v[102:105]
	v_lshl_add_u64 v[206:207], v[206:207], 0, s[98:99]
	s_add_i32 m0, s8, 0x400
	v_mfma_f32_16x16x32_bf16 v[86:89], v[188:191], v[152:155], v[86:89]
	global_load_lds_dwordx4 v[208:209], off
	v_mfma_f32_16x16x32_bf16 v[70:73], v[188:191], v[156:159], v[70:73]
	v_lshl_add_u64 v[208:209], v[208:209], 0, s[98:99]
	s_setprio 0
	s_waitcnt lgkmcnt(4)
	v_mfma_f32_16x16x32_bf16 v[114:117], v[192:195], v[144:147], v[114:117]
	v_mfma_f32_16x16x32_bf16 v[98:101], v[192:195], v[148:151], v[98:101]
	v_mfma_f32_16x16x32_bf16 v[82:85], v[192:195], v[152:155], v[82:85]
	v_mfma_f32_16x16x32_bf16 v[66:69], v[192:195], v[156:159], v[66:69]
	s_waitcnt vmcnt(6) lgkmcnt(0)
	s_barrier
	s_add_i32 s9, s6, 0x6000
	s_cmp_eq_u32 s6, 0xc000
	s_cselect_b32 s6, 0, s9
	v_add_u32_e32 v196, s6, v143
	v_add_u32_e32 v197, s6, v0
	v_mfma_f32_16x16x32_bf16 v[62:65], v[180:183], v[164:167], v[62:65]
	ds_read_b128 v[144:147], v196
	v_mfma_f32_16x16x32_bf16 v[46:49], v[180:183], v[168:171], v[46:49]
	ds_read_b128 v[148:151], v196 offset:1024
	v_mfma_f32_16x16x32_bf16 v[30:33], v[180:183], v[172:175], v[30:33]
	ds_read_b128 v[152:155], v196 offset:2048
	v_mfma_f32_16x16x32_bf16 v[14:17], v[180:183], v[176:179], v[14:17]
	ds_read_b128 v[156:159], v196 offset:3072
	ds_read_b128 v[180:183], v197 offset:16384
	v_mfma_f32_16x16x32_bf16 v[58:61], v[184:187], v[164:167], v[58:61]
	v_mfma_f32_16x16x32_bf16 v[42:45], v[184:187], v[168:171], v[42:45]
	v_mfma_f32_16x16x32_bf16 v[26:29], v[184:187], v[172:175], v[26:29]
	v_mfma_f32_16x16x32_bf16 v[10:13], v[184:187], v[176:179], v[10:13]
	ds_read_b128 v[184:187], v197 offset:17408
	v_mfma_f32_16x16x32_bf16 v[54:57], v[188:191], v[164:167], v[54:57]
	v_mfma_f32_16x16x32_bf16 v[38:41], v[188:191], v[168:171], v[38:41]
	v_mfma_f32_16x16x32_bf16 v[22:25], v[188:191], v[172:175], v[22:25]
	v_mfma_f32_16x16x32_bf16 v[6:9], v[188:191], v[176:179], v[6:9]
	ds_read_b128 v[188:191], v197 offset:18432
	v_mfma_f32_16x16x32_bf16 v[50:53], v[192:195], v[164:167], v[50:53]
	v_mfma_f32_16x16x32_bf16 v[34:37], v[192:195], v[168:171], v[34:37]
	v_mfma_f32_16x16x32_bf16 v[18:21], v[192:195], v[172:175], v[18:21]
	v_mfma_f32_16x16x32_bf16 v[2:5], v[192:195], v[176:179], v[2:5]
	ds_read_b128 v[192:195], v197 offset:19456
	s_sub_i32 s1, s1, 1
	s_cmp_lg_u32 s1, 0
	s_cbranch_scc1 .Lpipe_zgemm
	v_add_u32_e32 v160, s6, v143
	ds_read_b128 v[164:167], v160 offset:4096
	ds_read_b128 v[168:171], v160 offset:5120
	ds_read_b128 v[172:175], v160 offset:6144
	ds_read_b128 v[176:179], v160 offset:7168
	s_add_i32 s8, s6, 0xffffa000
	s_cmp_eq_u32 s6, 0
	s_cselect_b32 s8, 0xc000, s8
	s_add_i32 s9, s8, s7
	s_add_i32 s8, s8, s0
	s_mov_b32 m0, s9
	s_waitcnt lgkmcnt(7)
	v_mfma_f32_16x16x32_bf16 v[126:129], v[180:183], v[144:147], v[126:129]
	global_load_lds_dwordx4 v[198:199], off
	v_mfma_f32_16x16x32_bf16 v[110:113], v[180:183], v[148:151], v[110:113]
	v_lshl_add_u64 v[198:199], v[198:199], 0, s[98:99]
	s_add_i32 m0, s9, 0x400
	v_mfma_f32_16x16x32_bf16 v[94:97], v[180:183], v[152:155], v[94:97]
	global_load_lds_dwordx4 v[200:201], off
	v_mfma_f32_16x16x32_bf16 v[78:81], v[180:183], v[156:159], v[78:81]
	v_lshl_add_u64 v[200:201], v[200:201], 0, s[98:99]
	s_add_i32 m0, s9, 0x800
	s_waitcnt lgkmcnt(6)
	v_mfma_f32_16x16x32_bf16 v[122:125], v[184:187], v[144:147], v[122:125]
	global_load_lds_dwordx4 v[202:203], off
	v_mfma_f32_16x16x32_bf16 v[106:109], v[184:187], v[148:151], v[106:109]
	v_lshl_add_u64 v[202:203], v[202:203], 0, s[98:99]
	s_add_i32 m0, s9, 0xc00
	v_mfma_f32_16x16x32_bf16 v[90:93], v[184:187], v[152:155], v[90:93]
	global_load_lds_dwordx4 v[204:205], off
	v_mfma_f32_16x16x32_bf16 v[74:77], v[184:187], v[156:159], v[74:77]
	v_lshl_add_u64 v[204:205], v[204:205], 0, s[98:99]
	s_mov_b32 m0, s8
	s_waitcnt lgkmcnt(5)
; template <int MI, int NI>
; DI void gemm256(f32x4 (&acc)[MI][NI], const u16* __restrict__ A, int lda, const u16* __restrict__ Bt, int ldb, int K, int m0, int n0, char* smem) {
;     ...
;   for (int kt = 0; kt < nk; ++kt) {
;     if (kt + 1 < nk) asm volatile("s_waitcnt vmcnt(%0) lgkmcnt(0)" :: "n"(LPS) : "memory");
;     else asm volatile("s_waitcnt vmcnt(0) lgkmcnt(0)" ::: "memory");
;     __builtin_amdgcn_s_barrier();
;     __builtin_amdgcn_s_setprio(1);
;     const char* sb = smem + st * STAGE + foff;
;     bf16x8 af[MI], bfr[NI];
; #pragma unroll
;     for (int mi = 0; mi < MI; ++mi) af[mi] = *(const bf16x8*)(sb + (wr * MI + mi) * 1024);
; #pragma unroll
;     for (int ni = 0; ni < NI; ++ni) bfr[ni] = *(const bf16x8*)(sb + ABYTES + (wc * NI + ni) * 1024);
;     __builtin_amdgcn_sched_barrier(0x0);
;     if (kt + 2 < nk) { const int s2 = st >= 1 ? st - 1 : 2; G256_ISSUE(s2, (kt + 2) * 32); }
;     __builtin_amdgcn_s_setprio(0);
; #pragma unroll
;     for (int mi = 0; mi < MI; ++mi)
; #pragma unroll
;       for (int ni = 0; ni < NI; ++ni)
;         acc[mi][ni] = __builtin_amdgcn_mfma_f32_16x16x32_bf16(bfr[ni], af[mi], acc[mi][ni], 0, 0, 0);
;     st = st == 2 ? 0 : st + 1;
;   }
;   asm volatile("s_waitcnt lgkmcnt(0)" ::: "memory");
;   __builtin_amdgcn_s_barrier();
	v_mfma_f32_16x16x32_bf16 v[118:121], v[188:191], v[144:147], v[118:121]
	global_load_lds_dwordx4 v[206:207], off
	v_mfma_f32_16x16x32_bf16 v[102:105], v[188:191], v[148:151], v[102:105]
	v_lshl_add_u64 v[206:207], v[206:207], 0, s[98:99]
	s_add_i32 m0, s8, 0x400
	v_mfma_f32_16x16x32_bf16 v[86:89], v[188:191], v[152:155], v[86:89]
	global_load_lds_dwordx4 v[208:209], off
	v_mfma_f32_16x16x32_bf16 v[70:73], v[188:191], v[156:159], v[70:73]
	v_lshl_add_u64 v[208:209], v[208:209], 0, s[98:99]
	s_waitcnt lgkmcnt(4)
	v_mfma_f32_16x16x32_bf16 v[114:117], v[192:195], v[144:147], v[114:117]
	v_mfma_f32_16x16x32_bf16 v[98:101], v[192:195], v[148:151], v[98:101]
	v_mfma_f32_16x16x32_bf16 v[82:85], v[192:195], v[152:155], v[82:85]
	v_mfma_f32_16x16x32_bf16 v[66:69], v[192:195], v[156:159], v[66:69]
	s_waitcnt lgkmcnt(0)
	v_mfma_f32_16x16x32_bf16 v[62:65], v[180:183], v[164:167], v[62:65]
	v_mfma_f32_16x16x32_bf16 v[46:49], v[180:183], v[168:171], v[46:49]
	v_mfma_f32_16x16x32_bf16 v[30:33], v[180:183], v[172:175], v[30:33]
	v_mfma_f32_16x16x32_bf16 v[14:17], v[180:183], v[176:179], v[14:17]
	v_mfma_f32_16x16x32_bf16 v[58:61], v[184:187], v[164:167], v[58:61]
	v_mfma_f32_16x16x32_bf16 v[42:45], v[184:187], v[168:171], v[42:45]
	v_mfma_f32_16x16x32_bf16 v[26:29], v[184:187], v[172:175], v[26:29]
	v_mfma_f32_16x16x32_bf16 v[10:13], v[184:187], v[176:179], v[10:13]
	v_mfma_f32_16x16x32_bf16 v[54:57], v[188:191], v[164:167], v[54:57]
	v_mfma_f32_16x16x32_bf16 v[38:41], v[188:191], v[168:171], v[38:41]
	v_mfma_f32_16x16x32_bf16 v[22:25], v[188:191], v[172:175], v[22:25]
	v_mfma_f32_16x16x32_bf16 v[6:9], v[188:191], v[176:179], v[6:9]
	v_mfma_f32_16x16x32_bf16 v[50:53], v[192:195], v[164:167], v[50:53]
	v_mfma_f32_16x16x32_bf16 v[34:37], v[192:195], v[168:171], v[34:37]
	v_mfma_f32_16x16x32_bf16 v[18:21], v[192:195], v[172:175], v[18:21]
	v_mfma_f32_16x16x32_bf16 v[2:5], v[192:195], v[176:179], v[2:5]
	s_waitcnt vmcnt(6) lgkmcnt(0)
	s_barrier
	s_setprio 1
	v_add_u32_e32 v0, v140, v142
	ds_read_b128 v[130:133], v0
	ds_read_b128 v[142:145], v0 offset:1024
	ds_read_b128 v[146:149], v0 offset:2048
	ds_read_b128 v[150:153], v0 offset:3072
	ds_read_b128 v[154:157], v0 offset:4096
	ds_read_b128 v[158:161], v0 offset:5120
	ds_read_b128 v[164:167], v0 offset:6144
	ds_read_b128 v[168:171], v0 offset:7168
	v_add_u32_e32 v220, v140, v141
	ds_read_b128 v[138:141], v220 offset:16384
	ds_read_b128 v[172:175], v220 offset:17408
	ds_read_b128 v[176:179], v220 offset:18432
	ds_read_b128 v[180:183], v220 offset:19456
	s_setprio 0
	s_waitcnt lgkmcnt(3)
	v_mfma_f32_16x16x32_bf16 v[126:129], v[138:141], v[130:133], v[126:129]
	s_waitcnt vmcnt(0) lgkmcnt(0)
	s_barrier
	s_waitcnt lgkmcnt(2)
	v_mfma_f32_16x16x32_bf16 v[122:125], v[172:175], v[130:133], v[122:125]
	s_waitcnt lgkmcnt(1)
	v_mfma_f32_16x16x32_bf16 v[118:121], v[176:179], v[130:133], v[118:121]
	s_waitcnt lgkmcnt(0)
	v_mfma_f32_16x16x32_bf16 v[130:133], v[180:183], v[130:133], v[114:117]
	v_mfma_f32_16x16x32_bf16 v[110:113], v[138:141], v[142:145], v[110:113]
	v_mfma_f32_16x16x32_bf16 v[102:105], v[176:179], v[142:145], v[102:105]
	v_mfma_f32_16x16x32_bf16 v[94:97], v[138:141], v[146:149], v[94:97]
	v_mfma_f32_16x16x32_bf16 v[86:89], v[176:179], v[146:149], v[86:89]
	v_mfma_f32_16x16x32_bf16 v[78:81], v[138:141], v[150:153], v[78:81]
	v_mfma_f32_16x16x32_bf16 v[70:73], v[176:179], v[150:153], v[70:73]
	v_mfma_f32_16x16x32_bf16 v[62:65], v[138:141], v[154:157], v[62:65]
	v_mfma_f32_16x16x32_bf16 v[54:57], v[176:179], v[154:157], v[54:57]
	v_mfma_f32_16x16x32_bf16 v[46:49], v[138:141], v[158:161], v[46:49]
	v_mfma_f32_16x16x32_bf16 v[38:41], v[176:179], v[158:161], v[38:41]
	v_mfma_f32_16x16x32_bf16 v[30:33], v[138:141], v[164:167], v[30:33]
	v_mfma_f32_16x16x32_bf16 v[22:25], v[176:179], v[164:167], v[22:25]
	v_mfma_f32_16x16x32_bf16 v[14:17], v[138:141], v[168:171], v[14:17]
	v_mfma_f32_16x16x32_bf16 v[6:9], v[176:179], v[168:171], v[6:9]
	v_mfma_f32_16x16x32_bf16 v[184:187], v[172:175], v[142:145], v[106:109]
	v_mfma_f32_16x16x32_bf16 v[142:145], v[180:183], v[142:145], v[98:101]
	v_mfma_f32_16x16x32_bf16 v[188:191], v[172:175], v[146:149], v[90:93]
	v_mfma_f32_16x16x32_bf16 v[146:149], v[180:183], v[146:149], v[82:85]
	v_mfma_f32_16x16x32_bf16 v[192:195], v[172:175], v[150:153], v[74:77]
	v_mfma_f32_16x16x32_bf16 v[150:153], v[180:183], v[150:153], v[66:69]
	v_mfma_f32_16x16x32_bf16 v[196:199], v[172:175], v[154:157], v[58:61]
	v_mfma_f32_16x16x32_bf16 v[154:157], v[180:183], v[154:157], v[50:53]
	v_mfma_f32_16x16x32_bf16 v[200:203], v[172:175], v[158:161], v[42:45]
	v_mfma_f32_16x16x32_bf16 v[158:161], v[180:183], v[158:161], v[34:37]
	v_mfma_f32_16x16x32_bf16 v[204:207], v[172:175], v[164:167], v[26:29]
	v_mfma_f32_16x16x32_bf16 v[164:167], v[180:183], v[164:167], v[18:21]
	v_mfma_f32_16x16x32_bf16 v[138:141], v[172:175], v[168:171], v[10:13]
	v_mfma_f32_16x16x32_bf16 v[168:171], v[180:183], v[168:171], v[2:5]
	s_setprio 1
	s_nop 1
	ds_read_b128 v[2:5], v0 offset:24576
	ds_read_b128 v[10:13], v0 offset:25600
	ds_read_b128 v[18:21], v0 offset:26624
	ds_read_b128 v[26:29], v0 offset:27648
	ds_read_b128 v[34:37], v0 offset:28672
	ds_read_b128 v[172:175], v0 offset:29696
	ds_read_b128 v[176:179], v0 offset:30720
	ds_read_b128 v[180:183], v0 offset:31744
	ds_read_b128 v[208:211], v220 offset:40960
	ds_read_b128 v[212:215], v220 offset:41984
	ds_read_b128 v[216:219], v220 offset:43008
	ds_read_b128 v[220:223], v220 offset:44032
	s_setprio 0
	s_waitcnt lgkmcnt(3)
	v_mfma_f32_16x16x32_bf16 v[224:227], v[208:211], v[2:5], v[126:129]
	v_mov_b32_e32 v0, v136
	s_waitcnt lgkmcnt(0)
	s_barrier
; DI unsigned pack2(float a, float b) { float2_t v = {a, b}; bf16x2_t r = __builtin_convertvector(v, bf16x2_t); return __builtin_bit_cast(unsigned, r); }
; #define EPI_BEGIN const int lr1_ = launder_v(lr), lq1_ = launder_v(lq), wr1_ = launder_v(wr), wc1_ = launder_v(wc); { const int lr = lr1_, lq = lq1_, wr = wr1_, wc = wc1_; (void)lr; (void)lq; (void)wr; (void)wc;
; template <int MI, int NI>
; DI void gemm256(f32x4 (&acc)[MI][NI], const u16* __restrict__ A, int lda, const u16* __restrict__ Bt, int ldb, int K, int m0, int n0, char* smem) {
;     ...
; #pragma unroll
;     for (int mi = 0; mi < MI; ++mi)
; #pragma unroll
;       for (int ni = 0; ni < NI; ++ni)
;         acc[mi][ni] = __builtin_amdgcn_mfma_f32_16x16x32_bf16(bfr[ni], af[mi], acc[mi][ni], 0, 0, 0);
; DI void phase_zgemm(const Params& p, int l, char* smem) {
;     ...
;     EPI_BEGIN
; #pragma unroll
;     for (int mi = 0; mi < 8; mi += 2) {
;       const int m = m0 + wr * 128 + (mi + (lq & 1)) * 16 + lr;
; #pragma unroll
;       for (int ni = 0; ni < 4; ++ni) {
;         const int n = n0 + wc * 64 + ni * 16 + (lq >> 1) * 8;
;         const uint4 v = widen16(make_uint2(pack2(acc[mi][ni][0], acc[mi][ni][1]), pack2(acc[mi][ni][2], acc[mi][ni][3])),
;                                 make_uint2(pack2(acc[mi + 1][ni][0], acc[mi + 1][ni][1]), pack2(acc[mi + 1][ni][2], acc[mi + 1][ni][3])));
;         if (n < ZA) *(uint4*)(za + (size_t)m * ZA + n) = v;
;         else if (n < ZA + ZR) *(uint4*)(zr + (size_t)m * ZR + (n - ZA)) = v;
;       }
	s_waitcnt lgkmcnt(2)
	v_mfma_f32_16x16x32_bf16 v[114:117], v[212:215], v[2:5], v[122:125]
	s_movk_i32 s0, 0x900
	s_waitcnt lgkmcnt(1)
	v_mfma_f32_16x16x32_bf16 v[106:109], v[216:219], v[2:5], v[118:121]
	s_nop 0
	v_cvt_pk_bf16_f32 v122, v224, v225
	v_cvt_pk_bf16_f32 v123, v226, v227
	s_waitcnt lgkmcnt(0)
	v_mfma_f32_16x16x32_bf16 v[98:101], v[220:223], v[2:5], v[130:133]
	v_mov_b32_e32 v2, v137
	v_mov_b32_e32 v3, v134
	v_mov_b32_e32 v4, v135
	v_lshlrev_b32_e32 v3, 7, v3
	v_add3_u32 v132, v0, s5, v3
	v_lshlrev_b32_e32 v3, 2, v2
	v_and_b32_e32 v3, -8, v3
	v_lshlrev_b32_e32 v0, 6, v4
	v_add3_u32 v126, v3, s4, v0
	v_lshlrev_b32_e32 v0, 4, v2
	v_mfma_f32_16x16x32_bf16 v[228:231], v[208:211], v[10:13], v[110:113]
	v_and_b32_e32 v133, 16, v0
	v_add_u32_e32 v0, v132, v133
	v_mfma_f32_16x16x32_bf16 v[118:121], v[212:215], v[10:13], v[184:187]
	v_mfma_f32_16x16x32_bf16 v[110:113], v[216:219], v[10:13], v[102:105]
	s_nop 3
	v_cvt_pk_bf16_f32 v124, v228, v229
	v_cvt_pk_bf16_f32 v125, v230, v231
	s_nop 0
	v_permlane16_swap_b32_e32 v122, v124
	v_mfma_f32_16x16x32_bf16 v[102:105], v[220:223], v[10:13], v[142:145]
	v_permlane16_swap_b32_e32 v123, v125
	v_mfma_f32_16x16x32_bf16 v[10:13], v[216:219], v[176:179], v[22:25]
	s_nop 2
	v_mov_b64_e32 v[22:23], s[62:63]
	v_mfma_f32_16x16x32_bf16 v[90:93], v[208:211], v[18:21], v[94:97]
	v_mad_i64_i32 v[128:129], s[0:1], v0, s0, v[22:23]
	s_movk_i32 s0, 0x39f
	v_mfma_f32_16x16x32_bf16 v[82:85], v[212:215], v[18:21], v[188:191]
	v_cmp_lt_i32_e64 s[0:1], s0, v126
	v_mfma_f32_16x16x32_bf16 v[74:77], v[216:219], v[18:21], v[86:89]
	v_mfma_f32_16x16x32_bf16 v[66:69], v[220:223], v[18:21], v[146:149]
	v_mfma_f32_16x16x32_bf16 v[94:97], v[208:211], v[26:29], v[78:81]
	v_mfma_f32_16x16x32_bf16 v[86:89], v[212:215], v[26:29], v[192:195]
	v_mfma_f32_16x16x32_bf16 v[78:81], v[216:219], v[26:29], v[70:73]
	v_mfma_f32_16x16x32_bf16 v[70:73], v[220:223], v[26:29], v[150:153]
	v_mfma_f32_16x16x32_bf16 v[58:61], v[208:211], v[34:37], v[62:65]
	v_mfma_f32_16x16x32_bf16 v[50:53], v[212:215], v[34:37], v[196:199]
	v_mfma_f32_16x16x32_bf16 v[42:45], v[216:219], v[34:37], v[54:57]
	v_mfma_f32_16x16x32_bf16 v[34:37], v[220:223], v[34:37], v[154:157]
	v_mfma_f32_16x16x32_bf16 v[62:65], v[208:211], v[172:175], v[46:49]
	v_mfma_f32_16x16x32_bf16 v[54:57], v[212:215], v[172:175], v[200:203]
	v_mfma_f32_16x16x32_bf16 v[46:49], v[216:219], v[172:175], v[38:41]
	v_mfma_f32_16x16x32_bf16 v[38:41], v[220:223], v[172:175], v[158:161]
	v_mfma_f32_16x16x32_bf16 v[26:29], v[208:211], v[176:179], v[30:33]
	v_mfma_f32_16x16x32_bf16 v[18:21], v[212:215], v[176:179], v[204:207]
	v_mfma_f32_16x16x32_bf16 v[2:5], v[220:223], v[176:179], v[164:167]
	v_mfma_f32_16x16x32_bf16 v[30:33], v[208:211], v[180:183], v[14:17]
	v_mfma_f32_16x16x32_bf16 v[22:25], v[212:215], v[180:183], v[138:141]
	v_mfma_f32_16x16x32_bf16 v[14:17], v[216:219], v[180:183], v[6:9]
	v_mfma_f32_16x16x32_bf16 v[6:9], v[220:223], v[180:183], v[168:171]
	s_and_saveexec_b64 s[4:5], s[0:1]
	s_xor_b64 s[4:5], exec, s[4:5]
	s_cbranch_execz .LBB0_862
	s_movk_i32 s6, 0x820
	v_cmp_gt_u32_e32 vcc, s6, v126
	s_and_saveexec_b64 s[6:7], vcc
	s_cbranch_execz .LBB0_861
	v_mov_b32_e32 v127, v1
	v_lshl_add_u64 v[130:131], v[126:127], 1, v[128:129]
	v_add_co_u32_e32 v130, vcc, 0x47e0000, v130
	s_nop 1
	v_addc_co_u32_e32 v131, vcc, 0, v131, vcc
	flat_store_dwordx4 v[130:131], v[122:125] offset:2240

; template <int MI, int NI>
; DI void gemm256(f32x4 (&acc)[MI][NI], const u16* __restrict__ A, int lda, const u16* __restrict__ Bt, int ldb, int K, int m0, int n0, char* smem) {
;     ...
;   for (int kt = 0; kt < nk; ++kt) {
;     if (kt + 1 < nk) asm volatile("s_waitcnt vmcnt(%0) lgkmcnt(0)" :: "n"(LPS) : "memory");
;     else asm volatile("s_waitcnt vmcnt(0) lgkmcnt(0)" ::: "memory");
;     __builtin_amdgcn_s_barrier();
;     __builtin_amdgcn_s_setprio(1);
;     const char* sb = smem + st * STAGE + foff;
;     bf16x8 af[MI], bfr[NI];
; #pragma unroll
;     for (int mi = 0; mi < MI; ++mi) af[mi] = *(const bf16x8*)(sb + (wr * MI + mi) * 1024);
; #pragma unroll
;     for (int ni = 0; ni < NI; ++ni) bfr[ni] = *(const bf16x8*)(sb + ABYTES + (wc * NI + ni) * 1024);
;     __builtin_amdgcn_sched_barrier(0x0);
;     if (kt + 2 < nk) { const int s2 = st >= 1 ? st - 1 : 2; G256_ISSUE(s2, (kt + 2) * 32); }
;     __builtin_amdgcn_s_setprio(0);
; #pragma unroll
;     for (int mi = 0; mi < MI; ++mi)
; #pragma unroll
;       for (int ni = 0; ni < NI; ++ni)
;         acc[mi][ni] = __builtin_amdgcn_mfma_f32_16x16x32_bf16(bfr[ni], af[mi], acc[mi][ni], 0, 0, 0);
;     st = st == 2 ? 0 : st + 1;
;   }
.Lpipe_mlp2:
	s_setprio 1
	v_add_u32_e32 v161, s11, v160
	ds_read_b128 v[156:159], v161 offset:4096
	ds_read_b128 v[164:167], v161 offset:5120
	ds_read_b128 v[168:171], v161 offset:6144
	ds_read_b128 v[172:175], v161 offset:7168
	s_add_i32 s12, s11, 0xffffa000
	s_cmp_eq_u32 s11, 0
	s_cselect_b32 s12, 0xc000, s12
	s_add_i32 s13, s12, s0
	s_add_i32 s12, s12, s1
	s_mov_b32 m0, s13
	s_waitcnt lgkmcnt(7)
	v_mfma_f32_16x16x32_bf16 v[126:129], v[176:179], v[140:143], v[126:129]
	global_load_lds_dwordx4 v[196:197], off
	v_mfma_f32_16x16x32_bf16 v[110:113], v[176:179], v[144:147], v[110:113]
	v_lshl_add_u64 v[196:197], v[196:197], 0, s[98:99]
	s_add_i32 m0, s13, 0x400
	v_mfma_f32_16x16x32_bf16 v[94:97], v[176:179], v[148:151], v[94:97]
	global_load_lds_dwordx4 v[198:199], off
	v_mfma_f32_16x16x32_bf16 v[78:81], v[176:179], v[152:155], v[78:81]
	v_lshl_add_u64 v[198:199], v[198:199], 0, s[98:99]
	s_add_i32 m0, s13, 0x800
	s_waitcnt lgkmcnt(6)
	v_mfma_f32_16x16x32_bf16 v[122:125], v[180:183], v[140:143], v[122:125]
	global_load_lds_dwordx4 v[200:201], off
	v_mfma_f32_16x16x32_bf16 v[106:109], v[180:183], v[144:147], v[106:109]
	v_lshl_add_u64 v[200:201], v[200:201], 0, s[98:99]
	s_add_i32 m0, s13, 0xc00
	v_mfma_f32_16x16x32_bf16 v[90:93], v[180:183], v[148:151], v[90:93]
	global_load_lds_dwordx4 v[202:203], off
	v_mfma_f32_16x16x32_bf16 v[74:77], v[180:183], v[152:155], v[74:77]
	v_lshl_add_u64 v[202:203], v[202:203], 0, s[98:99]
	s_mov_b32 m0, s12
	s_waitcnt lgkmcnt(5)
	v_mfma_f32_16x16x32_bf16 v[118:121], v[184:187], v[140:143], v[118:121]
	global_load_lds_dwordx4 v[204:205], off
	v_mfma_f32_16x16x32_bf16 v[102:105], v[184:187], v[144:147], v[102:105]
	v_lshl_add_u64 v[204:205], v[204:205], 0, s[98:99]
	s_add_i32 m0, s12, 0x400
	v_mfma_f32_16x16x32_bf16 v[86:89], v[184:187], v[148:151], v[86:89]
	global_load_lds_dwordx4 v[206:207], off
	v_mfma_f32_16x16x32_bf16 v[70:73], v[184:187], v[152:155], v[70:73]
	v_lshl_add_u64 v[206:207], v[206:207], 0, s[98:99]
	s_setprio 0
	s_waitcnt lgkmcnt(4)
	v_mfma_f32_16x16x32_bf16 v[114:117], v[188:191], v[140:143], v[114:117]
	v_mfma_f32_16x16x32_bf16 v[98:101], v[188:191], v[144:147], v[98:101]
	v_mfma_f32_16x16x32_bf16 v[82:85], v[188:191], v[148:151], v[82:85]
	v_mfma_f32_16x16x32_bf16 v[66:69], v[188:191], v[152:155], v[66:69]
	s_waitcnt vmcnt(6) lgkmcnt(0)
	s_barrier
	s_add_i32 s13, s11, 0x6000
	s_cmp_eq_u32 s11, 0xc000
	s_cselect_b32 s11, 0, s13
	v_add_u32_e32 v192, s11, v160
	v_add_u32_e32 v193, s11, v0
	v_mfma_f32_16x16x32_bf16 v[62:65], v[176:179], v[156:159], v[62:65]
	ds_read_b128 v[140:143], v192
	v_mfma_f32_16x16x32_bf16 v[46:49], v[176:179], v[164:167], v[46:49]
	ds_read_b128 v[144:147], v192 offset:1024
	v_mfma_f32_16x16x32_bf16 v[30:33], v[176:179], v[168:171], v[30:33]
	ds_read_b128 v[148:151], v192 offset:2048
	v_mfma_f32_16x16x32_bf16 v[14:17], v[176:179], v[172:175], v[14:17]
	ds_read_b128 v[152:155], v192 offset:3072
	ds_read_b128 v[176:179], v193 offset:16384
	v_mfma_f32_16x16x32_bf16 v[58:61], v[180:183], v[156:159], v[58:61]
	v_mfma_f32_16x16x32_bf16 v[42:45], v[180:183], v[164:167], v[42:45]
	v_mfma_f32_16x16x32_bf16 v[26:29], v[180:183], v[168:171], v[26:29]
	v_mfma_f32_16x16x32_bf16 v[10:13], v[180:183], v[172:175], v[10:13]
	ds_read_b128 v[180:183], v193 offset:17408
	v_mfma_f32_16x16x32_bf16 v[54:57], v[184:187], v[156:159], v[54:57]
	v_mfma_f32_16x16x32_bf16 v[38:41], v[184:187], v[164:167], v[38:41]
	v_mfma_f32_16x16x32_bf16 v[22:25], v[184:187], v[168:171], v[22:25]
	v_mfma_f32_16x16x32_bf16 v[6:9], v[184:187], v[172:175], v[6:9]
	ds_read_b128 v[184:187], v193 offset:18432
	v_mfma_f32_16x16x32_bf16 v[50:53], v[188:191], v[156:159], v[50:53]
	v_mfma_f32_16x16x32_bf16 v[34:37], v[188:191], v[164:167], v[34:37]
	v_mfma_f32_16x16x32_bf16 v[18:21], v[188:191], v[168:171], v[18:21]
	v_mfma_f32_16x16x32_bf16 v[2:5], v[188:191], v[172:175], v[2:5]
	ds_read_b128 v[188:191], v193 offset:19456
	s_sub_i32 s100, s100, 1
	s_cmp_lg_u32 s100, 0
	s_cbranch_scc1 .Lpipe_mlp2
	v_add_u32_e32 v161, s11, v160
	ds_read_b128 v[156:159], v161 offset:4096
	ds_read_b128 v[164:167], v161 offset:5120
	ds_read_b128 v[168:171], v161 offset:6144
	ds_read_b128 v[172:175], v161 offset:7168
	s_add_i32 s12, s11, 0xffffa000
	s_cmp_eq_u32 s11, 0
	s_cselect_b32 s12, 0xc000, s12
	s_add_i32 s13, s12, s0
	s_add_i32 s12, s12, s1
	s_mov_b32 m0, s13
	s_waitcnt lgkmcnt(7)
	v_mfma_f32_16x16x32_bf16 v[126:129], v[176:179], v[140:143], v[126:129]
	global_load_lds_dwordx4 v[196:197], off
	v_mfma_f32_16x16x32_bf16 v[110:113], v[176:179], v[144:147], v[110:113]
	v_lshl_add_u64 v[196:197], v[196:197], 0, s[98:99]
	s_add_i32 m0, s13, 0x400
	v_mfma_f32_16x16x32_bf16 v[94:97], v[176:179], v[148:151], v[94:97]
	global_load_lds_dwordx4 v[198:199], off
	v_mfma_f32_16x16x32_bf16 v[78:81], v[176:179], v[152:155], v[78:81]
	v_lshl_add_u64 v[198:199], v[198:199], 0, s[98:99]
	s_add_i32 m0, s13, 0x800
	s_waitcnt lgkmcnt(6)
	v_mfma_f32_16x16x32_bf16 v[122:125], v[180:183], v[140:143], v[122:125]
	global_load_lds_dwordx4 v[200:201], off
	v_mfma_f32_16x16x32_bf16 v[106:109], v[180:183], v[144:147], v[106:109]
	v_lshl_add_u64 v[200:201], v[200:201], 0, s[98:99]
	s_add_i32 m0, s13, 0xc00
	v_mfma_f32_16x16x32_bf16 v[90:93], v[180:183], v[148:151], v[90:93]
	global_load_lds_dwordx4 v[202:203], off
	v_mfma_f32_16x16x32_bf16 v[74:77], v[180:183], v[152:155], v[74:77]
	v_lshl_add_u64 v[202:203], v[202:203], 0, s[98:99]
	s_mov_b32 m0, s12
	s_waitcnt lgkmcnt(5)
; template <int MI, int NI>
; DI void gemm256(f32x4 (&acc)[MI][NI], const u16* __restrict__ A, int lda, const u16* __restrict__ Bt, int ldb, int K, int m0, int n0, char* smem) {
;     ...
;   for (int kt = 0; kt < nk; ++kt) {
;     if (kt + 1 < nk) asm volatile("s_waitcnt vmcnt(%0) lgkmcnt(0)" :: "n"(LPS) : "memory");
;     else asm volatile("s_waitcnt vmcnt(0) lgkmcnt(0)" ::: "memory");
;     __builtin_amdgcn_s_barrier();
;     __builtin_amdgcn_s_setprio(1);
;     const char* sb = smem + st * STAGE + foff;
;     bf16x8 af[MI], bfr[NI];
; #pragma unroll
;     for (int mi = 0; mi < MI; ++mi) af[mi] = *(const bf16x8*)(sb + (wr * MI + mi) * 1024);
; #pragma unroll
;     for (int ni = 0; ni < NI; ++ni) bfr[ni] = *(const bf16x8*)(sb + ABYTES + (wc * NI + ni) * 1024);
;     __builtin_amdgcn_sched_barrier(0x0);
;     if (kt + 2 < nk) { const int s2 = st >= 1 ? st - 1 : 2; G256_ISSUE(s2, (kt + 2) * 32); }
;     __builtin_amdgcn_s_setprio(0);
; #pragma unroll
;     for (int mi = 0; mi < MI; ++mi)
; #pragma unroll
;       for (int ni = 0; ni < NI; ++ni)
;         acc[mi][ni] = __builtin_amdgcn_mfma_f32_16x16x32_bf16(bfr[ni], af[mi], acc[mi][ni], 0, 0, 0);
;     st = st == 2 ? 0 : st + 1;
;   }
;   asm volatile("s_waitcnt lgkmcnt(0)" ::: "memory");
;   __builtin_amdgcn_s_barrier();
	v_mfma_f32_16x16x32_bf16 v[118:121], v[184:187], v[140:143], v[118:121]
	global_load_lds_dwordx4 v[204:205], off
	v_mfma_f32_16x16x32_bf16 v[102:105], v[184:187], v[144:147], v[102:105]
	v_lshl_add_u64 v[204:205], v[204:205], 0, s[98:99]
	s_add_i32 m0, s12, 0x400
	v_mfma_f32_16x16x32_bf16 v[86:89], v[184:187], v[148:151], v[86:89]
	global_load_lds_dwordx4 v[206:207], off
	v_mfma_f32_16x16x32_bf16 v[70:73], v[184:187], v[152:155], v[70:73]
	v_lshl_add_u64 v[206:207], v[206:207], 0, s[98:99]
	s_waitcnt lgkmcnt(4)
	v_mfma_f32_16x16x32_bf16 v[114:117], v[188:191], v[140:143], v[114:117]
	v_mfma_f32_16x16x32_bf16 v[98:101], v[188:191], v[144:147], v[98:101]
	v_mfma_f32_16x16x32_bf16 v[82:85], v[188:191], v[148:151], v[82:85]
	v_mfma_f32_16x16x32_bf16 v[66:69], v[188:191], v[152:155], v[66:69]
	s_waitcnt lgkmcnt(0)
	v_mfma_f32_16x16x32_bf16 v[62:65], v[176:179], v[156:159], v[62:65]
	v_mfma_f32_16x16x32_bf16 v[46:49], v[176:179], v[164:167], v[46:49]
	v_mfma_f32_16x16x32_bf16 v[30:33], v[176:179], v[168:171], v[30:33]
	v_mfma_f32_16x16x32_bf16 v[14:17], v[176:179], v[172:175], v[14:17]
	v_mfma_f32_16x16x32_bf16 v[58:61], v[180:183], v[156:159], v[58:61]
	v_mfma_f32_16x16x32_bf16 v[42:45], v[180:183], v[164:167], v[42:45]
	v_mfma_f32_16x16x32_bf16 v[26:29], v[180:183], v[168:171], v[26:29]
	v_mfma_f32_16x16x32_bf16 v[10:13], v[180:183], v[172:175], v[10:13]
	v_mfma_f32_16x16x32_bf16 v[54:57], v[184:187], v[156:159], v[54:57]
	v_mfma_f32_16x16x32_bf16 v[38:41], v[184:187], v[164:167], v[38:41]
	v_mfma_f32_16x16x32_bf16 v[22:25], v[184:187], v[168:171], v[22:25]
	v_mfma_f32_16x16x32_bf16 v[6:9], v[184:187], v[172:175], v[6:9]
	v_mfma_f32_16x16x32_bf16 v[50:53], v[188:191], v[156:159], v[50:53]
	v_mfma_f32_16x16x32_bf16 v[34:37], v[188:191], v[164:167], v[34:37]
	v_mfma_f32_16x16x32_bf16 v[18:21], v[188:191], v[168:171], v[18:21]
	v_mfma_f32_16x16x32_bf16 v[2:5], v[188:191], v[172:175], v[2:5]
	s_mov_b32 s10, 0
	s_waitcnt vmcnt(6) lgkmcnt(0)
	s_barrier
	s_setprio 1
	s_mul_i32 s0, s10, 0x6000
	v_or_b32_e32 v0, s0, v138
	v_add_u32_e32 v136, v0, v139
	ds_read_b128 v[130:133], v136
	ds_read_b128 v[140:143], v136 offset:1024
	ds_read_b128 v[144:147], v136 offset:2048
	ds_read_b128 v[148:151], v136 offset:3072
	ds_read_b128 v[152:155], v136 offset:4096
	ds_read_b128 v[156:159], v136 offset:5120
	ds_read_b128 v[164:167], v136 offset:6144
	ds_read_b128 v[168:171], v136 offset:7168
	v_add_u32_e32 v0, v0, v135
	ds_read_b128 v[172:175], v0 offset:16384
	ds_read_b128 v[176:179], v0 offset:17408
	ds_read_b128 v[180:183], v0 offset:18432
	ds_read_b128 v[184:187], v0 offset:19456
	v_bfe_u32 v0, v134, 6, 1
	s_setprio 0
	s_waitcnt vmcnt(0) lgkmcnt(0)
	s_waitcnt lgkmcnt(3)
	v_mfma_f32_16x16x32_bf16 v[126:129], v[172:175], v[130:133], v[126:129]
	v_ashrrev_i32_e32 v160, 7, v134
	v_and_b32_e32 v161, 15, v134
	v_bfe_u32 v134, v134, 4, 2
	s_waitcnt lgkmcnt(2)
	v_mfma_f32_16x16x32_bf16 v[122:125], v[176:179], v[130:133], v[122:125]
	s_barrier
	s_waitcnt lgkmcnt(1)
	v_mfma_f32_16x16x32_bf16 v[118:121], v[180:183], v[130:133], v[118:121]
	s_waitcnt lgkmcnt(0)
	v_mfma_f32_16x16x32_bf16 v[114:117], v[184:187], v[130:133], v[114:117]
	v_mfma_f32_16x16x32_bf16 v[110:113], v[172:175], v[140:143], v[110:113]
	v_mfma_f32_16x16x32_bf16 v[106:109], v[176:179], v[140:143], v[106:109]
	v_mfma_f32_16x16x32_bf16 v[102:105], v[180:183], v[140:143], v[102:105]
	v_mfma_f32_16x16x32_bf16 v[98:101], v[184:187], v[140:143], v[98:101]
	v_mfma_f32_16x16x32_bf16 v[94:97], v[172:175], v[144:147], v[94:97]
	v_mfma_f32_16x16x32_bf16 v[90:93], v[176:179], v[144:147], v[90:93]
	v_mfma_f32_16x16x32_bf16 v[86:89], v[180:183], v[144:147], v[86:89]
	v_mfma_f32_16x16x32_bf16 v[82:85], v[184:187], v[144:147], v[82:85]
	v_mfma_f32_16x16x32_bf16 v[78:81], v[172:175], v[148:151], v[78:81]
	v_mfma_f32_16x16x32_bf16 v[130:133], v[176:179], v[148:151], v[74:77]
	v_mfma_f32_16x16x32_bf16 v[70:73], v[180:183], v[148:151], v[70:73]
	v_mfma_f32_16x16x32_bf16 v[66:69], v[184:187], v[148:151], v[66:69]
	v_mfma_f32_16x16x32_bf16 v[62:65], v[172:175], v[152:155], v[62:65]
	v_mfma_f32_16x16x32_bf16 v[58:61], v[176:179], v[152:155], v[58:61]
	v_mfma_f32_16x16x32_bf16 v[54:57], v[180:183], v[152:155], v[54:57]
	v_mfma_f32_16x16x32_bf16 v[50:53], v[184:187], v[152:155], v[50:53]
	v_mfma_f32_16x16x32_bf16 v[46:49], v[172:175], v[156:159], v[46:49]
	v_mfma_f32_16x16x32_bf16 v[42:45], v[176:179], v[156:159], v[42:45]
	v_mfma_f32_16x16x32_bf16 v[38:41], v[180:183], v[156:159], v[38:41]
	v_mfma_f32_16x16x32_bf16 v[34:37], v[184:187], v[156:159], v[34:37]
	v_mfma_f32_16x16x32_bf16 v[30:33], v[172:175], v[164:167], v[30:33]
	v_mfma_f32_16x16x32_bf16 v[26:29], v[176:179], v[164:167], v[26:29]
	v_mfma_f32_16x16x32_bf16 v[22:25], v[180:183], v[164:167], v[22:25]
	v_mfma_f32_16x16x32_bf16 v[18:21], v[184:187], v[164:167], v[18:21]
	v_mfma_f32_16x16x32_bf16 v[14:17], v[172:175], v[168:171], v[14:17]
	v_mfma_f32_16x16x32_bf16 v[10:13], v[176:179], v[168:171], v[10:13]
	v_mfma_f32_16x16x32_bf16 v[6:9], v[180:183], v[168:171], v[6:9]
	v_mfma_f32_16x16x32_bf16 v[140:143], v[184:187], v[168:171], v[2:5]
	s_setprio 1
	s_addk_i32 s0, 0x6000
	s_cmp_lg_u32 s10, 2
	s_cselect_b32 s0, s0, 0
	v_or_b32_e32 v168, s0, v138
	v_add_u32_e32 v164, v168, v139
	ds_read_b128 v[2:5], v164
	ds_read_b128 v[74:77], v164 offset:1024
	ds_read_b128 v[136:139], v164 offset:2048
	ds_read_b128 v[144:147], v164 offset:3072
	ds_read_b128 v[148:151], v164 offset:4096
	ds_read_b128 v[152:155], v164 offset:5120
	ds_read_b128 v[156:159], v164 offset:6144
	ds_read_b128 v[164:167], v164 offset:7168
	v_add_u32_e32 v135, v168, v135
	ds_read_b128 v[168:171], v135 offset:16384
	ds_read_b128 v[172:175], v135 offset:17408
	ds_read_b128 v[176:179], v135 offset:18432
	ds_read_b128 v[180:183], v135 offset:19456
	s_setprio 0
	s_waitcnt lgkmcnt(3)
	v_mfma_f32_16x16x32_bf16 v[126:129], v[168:171], v[2:5], v[126:129]
	s_waitcnt lgkmcnt(0)
	s_barrier
; template <int MI, int NI>
; DI void gemm256(f32x4 (&acc)[MI][NI], const u16* __restrict__ A, int lda, const u16* __restrict__ Bt, int ldb, int K, int m0, int n0, char* smem) {
;     ...
; #pragma unroll
;     for (int mi = 0; mi < MI; ++mi)
; #pragma unroll
;       for (int ni = 0; ni < NI; ++ni)
;         acc[mi][ni] = __builtin_amdgcn_mfma_f32_16x16x32_bf16(bfr[ni], af[mi], acc[mi][ni], 0, 0, 0);
; template <int MI, int NI>
; DI void resid_tile(const u16* A, int K, const u16* Bt, const float* gate, const float* xl_in, const float* xc_in, float* xl_out, float* xc_out,
;                    int m0, int n0, char* smem) {
;     ...
; #pragma unroll
;   for (int mi = 0; mi < MI; ++mi) {
;     const int m = m0 + wr * 16 * MI + mi * 16 + lr;
;     const int b9 = m < NTL ? m >> 12 : 8;
;     const float* xi = xrow(xl_in, xc_in, m);
;     float* xo = m < NTL ? xl_out + (size_t)m * D : xc_out + (size_t)(m - NTL) * D;
; #pragma unroll
;     for (int ni = 0; ni < NI; ++ni) {
;       const int n = n0 + wc * 16 * NI + ni * 16 + lq * 4;
;       const float4 g = *(const float4*)(gate + (size_t)b9 * 6144 + n);
;       const float4 xv = *(const float4*)(xi + n);
;       float4 ov;
;       ov.x = xv.x + g.x * acc[mi][ni][0]; ov.y = xv.y + g.y * acc[mi][ni][1]; ov.z = xv.z + g.z * acc[mi][ni][2]; ov.w = xv.w + g.w * acc[mi][ni][3];
;       *(float4*)(xo + n) = ov;
;     }
	s_waitcnt lgkmcnt(2)
	v_mfma_f32_16x16x32_bf16 v[122:125], v[172:175], v[2:5], v[122:125]
	s_waitcnt lgkmcnt(1)
	v_mfma_f32_16x16x32_bf16 v[184:187], v[176:179], v[2:5], v[118:121]
	v_lshlrev_b32_e32 v0, 6, v0
	s_waitcnt lgkmcnt(0)
	v_mfma_f32_16x16x32_bf16 v[188:191], v[180:183], v[2:5], v[114:117]
	v_lshlrev_b32_e32 v2, 7, v160
	v_mov_b32_e32 v118, s95
	v_mov_b32_e32 v119, s49
	v_add3_u32 v116, v161, s8, v2
	v_lshlrev_b32_e32 v2, 2, v134
	v_add3_u32 v2, v2, s9, v0
	v_min_i32_e32 v0, 0x8000, v116
	v_mfma_f32_16x16x32_bf16 v[110:113], v[168:171], v[74:77], v[110:113]
	v_ashrrev_i32_e32 v117, 31, v116
	v_cmp_gt_i32_e32 vcc, s58, v116
	v_mov_b32_e32 v120, s94
	v_mfma_f32_16x16x32_bf16 v[106:109], v[172:175], v[74:77], v[106:109]
	v_cndmask_b32_e32 v5, 0, v117, vcc
	v_mov_b32_e32 v121, s48
	v_cndmask_b32_e32 v115, v118, v119, vcc
	v_mfma_f32_16x16x32_bf16 v[102:105], v[176:179], v[74:77], v[102:105]
	v_cndmask_b32_e32 v114, v120, v121, vcc
	v_ashrrev_i32_e32 v3, 31, v2
	v_mfma_f32_16x16x32_bf16 v[98:101], v[180:183], v[74:77], v[98:101]
	v_mfma_f32_16x16x32_bf16 v[74:77], v[168:171], v[144:147], v[78:81]
	v_mfma_f32_16x16x32_bf16 v[78:81], v[172:175], v[144:147], v[130:133]
	s_nop 2
	v_ashrrev_i32_e32 v130, 12, v0
	v_add_u32_e32 v0, 0xffff8000, v116
	v_cndmask_b32_e32 v4, v0, v116, vcc
	v_lshlrev_b64 v[4:5], 12, v[4:5]
	v_lshl_add_u64 v[4:5], v[114:115], 0, v[4:5]
	v_mul_hi_i32_i24_e32 v115, 0x6000, v130
	v_mul_i32_i24_e32 v114, 0x6000, v130
	v_lshl_add_u64 v[130:131], s[82:83], 0, v[114:115]
	v_lshlrev_b64 v[114:115], 2, v[2:3]
	v_mfma_f32_16x16x32_bf16 v[94:97], v[168:171], v[136:139], v[94:97]
	v_lshl_add_u64 v[134:135], v[130:131], 0, v[114:115]
	v_mfma_f32_16x16x32_bf16 v[90:93], v[172:175], v[136:139], v[90:93]
	v_mfma_f32_16x16x32_bf16 v[86:89], v[176:179], v[136:139], v[86:89]
	v_mfma_f32_16x16x32_bf16 v[82:85], v[180:183], v[136:139], v[82:85]
	v_lshl_add_u64 v[136:137], v[4:5], 0, v[114:115]
	flat_load_dwordx4 v[2:5], v[134:135]
	flat_load_dwordx4 v[130:133], v[136:137]
	v_mfma_f32_16x16x32_bf16 v[70:73], v[176:179], v[144:147], v[70:73]
	v_lshlrev_b64 v[138:139], 12, v[116:117]
	v_lshl_add_u64 v[138:139], s[48:49], 0, v[138:139]
	s_waitcnt vmcnt(0) lgkmcnt(0)
	v_pk_fma_f32 v[2:3], v[126:127], v[2:3], v[130:131]
	v_mfma_f32_16x16x32_bf16 v[66:69], v[180:183], v[144:147], v[66:69]
	v_lshlrev_b64 v[144:145], 12, v[0:1]
	v_lshl_add_u64 v[144:145], s[94:95], 0, v[144:145]
	v_cndmask_b32_e32 v139, v145, v139, vcc
	v_cndmask_b32_e32 v138, v144, v138, vcc
	v_lshl_add_u64 v[138:139], v[138:139], 0, v[114:115]
	v_pk_fma_f32 v[4:5], v[128:129], v[4:5], v[132:133]
	flat_store_dwordx4 v[138:139], v[2:5]
	flat_load_dwordx4 v[126:129], v[134:135] offset:64
	flat_load_dwordx4 v[130:133], v[136:137] offset:64
	v_mfma_f32_16x16x32_bf16 v[2:5], v[172:175], v[164:167], v[10:13]
	v_mfma_f32_16x16x32_bf16 v[62:65], v[168:171], v[148:151], v[62:65]
	s_waitcnt vmcnt(0) lgkmcnt(0)
	s_nop 0
	v_pk_fma_f32 v[10:11], v[122:123], v[126:127], v[130:131]
	v_pk_fma_f32 v[12:13], v[124:125], v[128:129], v[132:133]
	flat_store_dwordx4 v[138:139], v[10:13] offset:64
	flat_load_dwordx4 v[10:13], v[134:135] offset:128
	s_nop 0
	flat_load_dwordx4 v[122:125], v[136:137] offset:128
	v_mfma_f32_16x16x32_bf16 v[58:61], v[172:175], v[148:151], v[58:61]
	s_waitcnt vmcnt(0) lgkmcnt(0)
	v_pk_fma_f32 v[10:11], v[184:185], v[10:11], v[122:123]
	v_pk_fma_f32 v[12:13], v[186:187], v[12:13], v[124:125]
	flat_store_dwordx4 v[138:139], v[10:13] offset:128
	flat_load_dwordx4 v[122:125], v[134:135] offset:192
	flat_load_dwordx4 v[126:129], v[136:137] offset:192
	v_mfma_f32_16x16x32_bf16 v[54:57], v[176:179], v[148:151], v[54:57]
	s_waitcnt vmcnt(0) lgkmcnt(0)
	v_pk_fma_f32 v[122:123], v[188:189], v[122:123], v[126:127]
	v_pk_fma_f32 v[124:125], v[190:191], v[124:125], v[128:129]
	v_mfma_f32_16x16x32_bf16 v[50:53], v[180:183], v[148:151], v[50:53]
	flat_store_dwordx4 v[138:139], v[122:125] offset:192
	v_mfma_f32_16x16x32_bf16 v[46:49], v[168:171], v[152:155], v[46:49]
	v_mfma_f32_16x16x32_bf16 v[42:45], v[172:175], v[152:155], v[42:45]
	v_mfma_f32_16x16x32_bf16 v[38:41], v[176:179], v[152:155], v[38:41]
	v_mfma_f32_16x16x32_bf16 v[34:37], v[180:183], v[152:155], v[34:37]
	v_mfma_f32_16x16x32_bf16 v[30:33], v[168:171], v[156:159], v[30:33]
	v_mfma_f32_16x16x32_bf16 v[26:29], v[172:175], v[156:159], v[26:29]
	v_mfma_f32_16x16x32_bf16 v[22:25], v[176:179], v[156:159], v[22:25]
	v_mfma_f32_16x16x32_bf16 v[18:21], v[180:183], v[156:159], v[18:21]
	v_mfma_f32_16x16x32_bf16 v[14:17], v[168:171], v[164:167], v[14:17]
	v_mfma_f32_16x16x32_bf16 v[6:9], v[176:179], v[164:167], v[6:9]
	v_mfma_f32_16x16x32_bf16 v[10:13], v[180:183], v[164:167], v[140:143]
	v_add_u32_e32 v122, 16, v116
	v_min_i32_e32 v0, 0x8000, v122
	v_cmp_gt_i32_e32 vcc, s58, v122
	v_ashrrev_i32_e32 v117, 12, v0
	v_add_u32_e32 v0, 0xffff8010, v116
	v_ashrrev_i32_e32 v123, 31, v122
	v_cndmask_b32_e32 v125, 0, v123, vcc
	v_cndmask_b32_e32 v124, v0, v122, vcc
	v_cndmask_b32_e32 v127, v118, v119, vcc
	v_cndmask_b32_e32 v126, v120, v121, vcc
	v_lshlrev_b64 v[124:125], 12, v[124:125]
	v_lshl_add_u64 v[124:125], v[126:127], 0, v[124:125]
	v_lshlrev_b64 v[122:123], 12, v[122:123]
	v_lshlrev_b64 v[126:127], 12, v[0:1]
	v_lshl_add_u64 v[122:123], s[48:49], 0, v[122:123]
	v_lshl_add_u64 v[126:127], s[94:95], 0, v[126:127]
	v_cndmask_b32_e32 v123, v127, v123, vcc
	v_cndmask_b32_e32 v122, v126, v122, vcc
	v_mul_hi_i32_i24_e32 v127, 0x6000, v117
	v_mul_i32_i24_e32 v126, 0x6000, v117
	v_lshl_add_u64 v[126:127], s[82:83], 0, v[126:127]
	v_lshl_add_u64 v[130:131], v[126:127], 0, v[114:115]
	v_lshl_add_u64 v[132:133], v[124:125], 0, v[114:115]
	v_lshl_add_u64 v[134:135], v[122:123], 0, v[114:115]
	global_load_dwordx4 v[156:159], v[130:131], off
	global_load_dwordx4 v[164:167], v[130:131], off offset:64
	global_load_dwordx4 v[168:171], v[130:131], off offset:128
	global_load_dwordx4 v[172:175], v[130:131], off offset:192
	global_load_dwordx4 v[140:143], v[132:133], off
	global_load_dwordx4 v[144:147], v[132:133], off offset:64
	global_load_dwordx4 v[148:151], v[132:133], off offset:128
	global_load_dwordx4 v[152:155], v[132:133], off offset:192
	v_mov_b32_e32 v216, 0x10000
	v_mov_b32_e32 v217, 0
	v_lshl_add_u64 v[212:213], v[132:133], 0, v[216:217]
	v_lshl_add_u64 v[214:215], v[134:135], 0, v[216:217]
	global_load_dwordx4 v[176:179], v[212:213], off
	global_load_dwordx4 v[180:183], v[212:213], off offset:64
	global_load_dwordx4 v[184:187], v[212:213], off offset:128
	global_load_dwordx4 v[188:191], v[212:213], off offset:192
	v_lshl_add_u64 v[212:213], v[212:213], 0, v[216:217]
	s_waitcnt vmcnt(4)
; template <int MI, int NI>
; DI void resid_tile(const u16* A, int K, const u16* Bt, const float* gate, const float* xl_in, const float* xc_in, float* xl_out, float* xc_out,
;                    int m0, int n0, char* smem) {
;     ...
; #pragma unroll
;   for (int mi = 0; mi < MI; ++mi) {
;     const int m = m0 + wr * 16 * MI + mi * 16 + lr;
;     const int b9 = m < NTL ? m >> 12 : 8;
;     const float* xi = xrow(xl_in, xc_in, m);
;     float* xo = m < NTL ? xl_out + (size_t)m * D : xc_out + (size_t)(m - NTL) * D;
; #pragma unroll
;     for (int ni = 0; ni < NI; ++ni) {
;       const int n = n0 + wc * 16 * NI + ni * 16 + lq * 4;
;       const float4 g = *(const float4*)(gate + (size_t)b9 * 6144 + n);
;       const float4 xv = *(const float4*)(xi + n);
;       float4 ov;
;       ov.x = xv.x + g.x * acc[mi][ni][0]; ov.y = xv.y + g.y * acc[mi][ni][1]; ov.z = xv.z + g.z * acc[mi][ni][2]; ov.w = xv.w + g.w * acc[mi][ni][3];
;       *(float4*)(xo + n) = ov;
;     }
; DI void phase_resid(const Params& p, const u16* A, int K, const u16* Bt, const float* gate  ,
;                     const float* xl_in, const float* xc_in, float* xl_out, float* xc_out, int Mout, char* smem) {
;     ...
;   for (int it = 0;; ++it) {
;     int tm, tn;
;     if (!tile_map(it, NTL / 256, 8, blk__, gridDim.x, tm, tn)) break;
;     resid_tile<8, 4>(A, K, Bt, gate, xl_in, xc_in, xl_out, xc_out, tm * 256, tn * 128, smem);
;   }
	v_pk_fma_f32 v[110:111], v[110:111], v[156:157], v[140:141]
	v_pk_fma_f32 v[112:113], v[112:113], v[158:159], v[142:143]
	v_pk_fma_f32 v[106:107], v[106:107], v[164:165], v[144:145]
	v_pk_fma_f32 v[108:109], v[108:109], v[166:167], v[146:147]
	v_pk_fma_f32 v[102:103], v[102:103], v[168:169], v[148:149]
	v_pk_fma_f32 v[104:105], v[104:105], v[170:171], v[150:151]
	v_pk_fma_f32 v[98:99], v[98:99], v[172:173], v[152:153]
	v_pk_fma_f32 v[100:101], v[100:101], v[174:175], v[154:155]
	global_store_dwordx4 v[134:135], v[110:113], off
	global_store_dwordx4 v[134:135], v[106:109], off offset:64
	global_store_dwordx4 v[134:135], v[102:105], off offset:128
	global_store_dwordx4 v[134:135], v[98:101], off offset:192
	global_load_dwordx4 v[140:143], v[212:213], off
	global_load_dwordx4 v[144:147], v[212:213], off offset:64
	global_load_dwordx4 v[148:151], v[212:213], off offset:128
	global_load_dwordx4 v[152:155], v[212:213], off offset:192
	v_lshl_add_u64 v[212:213], v[212:213], 0, v[216:217]
	s_waitcnt vmcnt(8)
	v_pk_fma_f32 v[94:95], v[94:95], v[156:157], v[176:177]
	v_pk_fma_f32 v[96:97], v[96:97], v[158:159], v[178:179]
	v_pk_fma_f32 v[90:91], v[90:91], v[164:165], v[180:181]
	v_pk_fma_f32 v[92:93], v[92:93], v[166:167], v[182:183]
	v_pk_fma_f32 v[86:87], v[86:87], v[168:169], v[184:185]
	v_pk_fma_f32 v[88:89], v[88:89], v[170:171], v[186:187]
	v_pk_fma_f32 v[82:83], v[82:83], v[172:173], v[188:189]
	v_pk_fma_f32 v[84:85], v[84:85], v[174:175], v[190:191]
	global_store_dwordx4 v[214:215], v[94:97], off
	global_store_dwordx4 v[214:215], v[90:93], off offset:64
	global_store_dwordx4 v[214:215], v[86:89], off offset:128
	global_store_dwordx4 v[214:215], v[82:85], off offset:192
	v_lshl_add_u64 v[214:215], v[214:215], 0, v[216:217]
	global_load_dwordx4 v[176:179], v[212:213], off
	global_load_dwordx4 v[180:183], v[212:213], off offset:64
	global_load_dwordx4 v[184:187], v[212:213], off offset:128
	global_load_dwordx4 v[188:191], v[212:213], off offset:192
	v_lshl_add_u64 v[212:213], v[212:213], 0, v[216:217]
	s_waitcnt vmcnt(8)
	v_pk_fma_f32 v[74:75], v[74:75], v[156:157], v[140:141]
	v_pk_fma_f32 v[76:77], v[76:77], v[158:159], v[142:143]
	v_pk_fma_f32 v[78:79], v[78:79], v[164:165], v[144:145]
	v_pk_fma_f32 v[80:81], v[80:81], v[166:167], v[146:147]
	v_pk_fma_f32 v[70:71], v[70:71], v[168:169], v[148:149]
	v_pk_fma_f32 v[72:73], v[72:73], v[170:171], v[150:151]
	v_pk_fma_f32 v[66:67], v[66:67], v[172:173], v[152:153]
	v_pk_fma_f32 v[68:69], v[68:69], v[174:175], v[154:155]
	global_store_dwordx4 v[214:215], v[74:77], off
	global_store_dwordx4 v[214:215], v[78:81], off offset:64
	global_store_dwordx4 v[214:215], v[70:73], off offset:128
	global_store_dwordx4 v[214:215], v[66:69], off offset:192
	v_lshl_add_u64 v[214:215], v[214:215], 0, v[216:217]
	global_load_dwordx4 v[140:143], v[212:213], off
	global_load_dwordx4 v[144:147], v[212:213], off offset:64
	global_load_dwordx4 v[148:151], v[212:213], off offset:128
	global_load_dwordx4 v[152:155], v[212:213], off offset:192
	v_lshl_add_u64 v[212:213], v[212:213], 0, v[216:217]
	s_waitcnt vmcnt(8)
	v_pk_fma_f32 v[62:63], v[62:63], v[156:157], v[176:177]
	v_pk_fma_f32 v[64:65], v[64:65], v[158:159], v[178:179]
	v_pk_fma_f32 v[58:59], v[58:59], v[164:165], v[180:181]
	v_pk_fma_f32 v[60:61], v[60:61], v[166:167], v[182:183]
	v_pk_fma_f32 v[54:55], v[54:55], v[168:169], v[184:185]
	v_pk_fma_f32 v[56:57], v[56:57], v[170:171], v[186:187]
	v_pk_fma_f32 v[50:51], v[50:51], v[172:173], v[188:189]
	v_pk_fma_f32 v[52:53], v[52:53], v[174:175], v[190:191]
	global_store_dwordx4 v[214:215], v[62:65], off
	global_store_dwordx4 v[214:215], v[58:61], off offset:64
	global_store_dwordx4 v[214:215], v[54:57], off offset:128
	global_store_dwordx4 v[214:215], v[50:53], off offset:192
	v_lshl_add_u64 v[214:215], v[214:215], 0, v[216:217]
	global_load_dwordx4 v[176:179], v[212:213], off
	global_load_dwordx4 v[180:183], v[212:213], off offset:64
	global_load_dwordx4 v[184:187], v[212:213], off offset:128
	global_load_dwordx4 v[188:191], v[212:213], off offset:192
	v_lshl_add_u64 v[212:213], v[212:213], 0, v[216:217]
	s_waitcnt vmcnt(8)
	v_pk_fma_f32 v[46:47], v[46:47], v[156:157], v[140:141]
	v_pk_fma_f32 v[48:49], v[48:49], v[158:159], v[142:143]
	v_pk_fma_f32 v[42:43], v[42:43], v[164:165], v[144:145]
	v_pk_fma_f32 v[44:45], v[44:45], v[166:167], v[146:147]
	v_pk_fma_f32 v[38:39], v[38:39], v[168:169], v[148:149]
	v_pk_fma_f32 v[40:41], v[40:41], v[170:171], v[150:151]
	v_pk_fma_f32 v[34:35], v[34:35], v[172:173], v[152:153]
	v_pk_fma_f32 v[36:37], v[36:37], v[174:175], v[154:155]
	global_store_dwordx4 v[214:215], v[46:49], off
	global_store_dwordx4 v[214:215], v[42:45], off offset:64
	global_store_dwordx4 v[214:215], v[38:41], off offset:128
	global_store_dwordx4 v[214:215], v[34:37], off offset:192
	v_lshl_add_u64 v[214:215], v[214:215], 0, v[216:217]
	global_load_dwordx4 v[140:143], v[212:213], off
	global_load_dwordx4 v[144:147], v[212:213], off offset:64
	global_load_dwordx4 v[148:151], v[212:213], off offset:128
	global_load_dwordx4 v[152:155], v[212:213], off offset:192
	s_waitcnt vmcnt(8)
	v_pk_fma_f32 v[30:31], v[30:31], v[156:157], v[176:177]
	v_pk_fma_f32 v[32:33], v[32:33], v[158:159], v[178:179]
	v_pk_fma_f32 v[26:27], v[26:27], v[164:165], v[180:181]
	v_pk_fma_f32 v[28:29], v[28:29], v[166:167], v[182:183]
	v_pk_fma_f32 v[22:23], v[22:23], v[168:169], v[184:185]
	v_pk_fma_f32 v[24:25], v[24:25], v[170:171], v[186:187]
	v_pk_fma_f32 v[18:19], v[18:19], v[172:173], v[188:189]
	v_pk_fma_f32 v[20:21], v[20:21], v[174:175], v[190:191]
	global_store_dwordx4 v[214:215], v[30:33], off
	global_store_dwordx4 v[214:215], v[26:29], off offset:64
	global_store_dwordx4 v[214:215], v[22:25], off offset:128
	global_store_dwordx4 v[214:215], v[18:21], off offset:192
	v_lshl_add_u64 v[214:215], v[214:215], 0, v[216:217]
	s_waitcnt vmcnt(4)
	v_pk_fma_f32 v[14:15], v[14:15], v[156:157], v[140:141]
	v_pk_fma_f32 v[16:17], v[16:17], v[158:159], v[142:143]
	v_pk_fma_f32 v[2:3], v[2:3], v[164:165], v[144:145]
	v_pk_fma_f32 v[4:5], v[4:5], v[166:167], v[146:147]
	v_pk_fma_f32 v[6:7], v[6:7], v[168:169], v[148:149]
	v_pk_fma_f32 v[8:9], v[8:9], v[170:171], v[150:151]
	v_pk_fma_f32 v[10:11], v[10:11], v[172:173], v[152:153]
	v_pk_fma_f32 v[12:13], v[12:13], v[174:175], v[154:155]
	global_store_dwordx4 v[214:215], v[14:17], off
	global_store_dwordx4 v[214:215], v[2:5], off offset:64
	global_store_dwordx4 v[214:215], v[6:9], off offset:128
	global_store_dwordx4 v[214:215], v[10:13], off offset:192
	s_add_i32 s7, s7, 1
	s_mul_i32 s0, s7, s39
	s_add_i32 s0, s0, s5
	s_cmpk_gt_i32 s0, 0x7f
	s_cbranch_scc0 .LBB0_961
